# P10: query fragment register sets alternate between tasks (no copy), accumulator rows cleared at read-back (one barrier and the zero fill less per unit)
# baseline (speedup 1.0000x reference)
.LBB0_1317:
	v_ashrrev_i32_e32 v219, 31, v218
	v_ashrrev_i32_e32 v215, 31, v214
	s_lshl_b32 s1, s10, 21
	s_add_u32 s8, s36, s1
	s_addc_u32 s9, s37, 0
	s_add_u32 s11, s40, s1
	s_addc_u32 s12, s41, 0
	s_movk_i32 s82, 0x660
	s_waitcnt vmcnt(0)
	v_lshlrev_b32_e32 v2, 4, v199
	v_mov_b32_e32 v22, v218
	v_and_b32_e32 v24, 31, v199
	v_mul_u32_u24_e32 v25, 43, v24
	v_lshrrev_b32_e32 v25, 8, v25
	v_mad_i32_i24 v24, v25, -6, v24
	v_and_b32_e32 v28, 31, v199
	v_cmp_gt_u32_e64 s[94:95], 30, v28
	v_lshlrev_b32_e64 v23, v25, 1
	v_cndmask_b32_e64 v25, 0, v25, s[94:95]
	v_mul_u32_u24_e32 v18, 6, v25
	v_mov_b32_e32 v19, 0x110
	v_mul_u32_u24_e32 v19, v19, v24
	v_lshl_add_u32 v19, v206, 2, v19
	v_add_u32_e32 v19, 0x4000, v19
	s_mul_i32 s0, s10, 6
	v_add_u32_e32 v20, s0, v24
	v_lshl_add_u32 v20, v20, 7, v210
	v_mov_b32_e32 v31, 0x110
	v_mul_u32_u24_e32 v31, v31, v24
	v_add_u32_e32 v31, 0x4100, v31
	v_add_u32_e32 v31, v31, v206
	s_lshl_b32 s90, s77, 8
	s_add_i32 s90, s90, 0x1e000
	s_cmp_eq_u32 s96, 1
	s_cbranch_scc0 .Lq_nozero
	v_mov_b32_e32 v82, 0
	v_mov_b32_e32 v83, 0
	v_mov_b32_e32 v84, 0
	v_mov_b32_e32 v85, 0
	s_lshl_b32 s0, s77, 10
	s_add_i32 s0, s0, 0x4000
	v_add_u32_e32 v28, s0, v2
	v_add_u32_e32 v29, 0x10000, v28
	ds_write_b128 v28, v[82:85]
	ds_write_b128 v28, v[82:85] offset:8192
	ds_write_b128 v28, v[82:85] offset:16384
	ds_write_b128 v28, v[82:85] offset:24576
	ds_write_b128 v28, v[82:85] offset:32768
	ds_write_b128 v28, v[82:85] offset:40960
	ds_write_b128 v28, v[82:85] offset:49152
	ds_write_b128 v28, v[82:85] offset:57344
	ds_write_b128 v29, v[82:85]
	ds_write_b128 v29, v[82:85] offset:8192
	ds_write_b128 v29, v[82:85] offset:16384
	ds_write_b128 v29, v[82:85] offset:24576
	ds_write_b128 v29, v[82:85] offset:32768
	v_mov_b32_e32 v86, 0x1800
	ds_write_b32 v86, v82
	ds_write_b64 v86, v[82:83] offset:8
	v_lshl_add_u32 v122, v199, 2, s90
	ds_write_b32 v122, v82
	s_waitcnt lgkmcnt(0)
	s_barrier
.Lq_nozero:
	v_and_b32_e32 v102, 31, v199
	s_lshl_b32 s0, s77, 5
	v_add_u32_e32 v103, s0, v102
	s_mov_b64 s[58:59], exec
	v_cmp_gt_u32_e32 vcc, 32, v199
	s_and_b64 exec, exec, vcc
	v_lshlrev_b32_e32 v106, 3, v103
	ds_read_b64 v[104:105], v106
	s_waitcnt lgkmcnt(0)
	v_bcnt_u32_b32 v107, v104, 0
	v_bcnt_u32_b32 v107, v105, v107
	v_add_u32_e32 v108, 4, v107
	v_mul_u32_u24_e32 v108, 0xcd, v108
	v_lshrrev_b32_e32 v108, 10, v108
	v_cmp_eq_u32_e64 s[92:93], 64, v107
	v_cndmask_b32_e64 v107, v107, 0, s[92:93]
	v_mov_b32_e32 v110, 0x1800
	ds_add_rtn_u32 v109, v110, v108
	s_waitcnt lgkmcnt(0)

.Lq_again:
	s_mov_b32 s52, 0
	s_mov_b32 s69, 0
	s_min_u32 s14, s69, 63
	s_nop 3
	v_readlane_b32 s30, v33, s14
	s_and_b32 s30, s30, 0xff
	s_lshl_b32 s30, s30, 13
	s_add_u32 s64, s11, s30
	s_addc_u32 s65, s12, 0
	s_add_u32 s66, s8, s30
	s_addc_u32 s67, s9, 0
	global_load_dwordx4 v[178:181], v2, s[64:65]
	global_load_dwordx4 v[174:177], v2, s[64:65] offset:1024
	global_load_dwordx4 v[170:173], v2, s[64:65] offset:2048
	global_load_dwordx4 v[166:169], v2, s[64:65] offset:3072
	global_load_dwordx4 v[146:149], v2, s[66:67]
	global_load_dwordx4 v[142:145], v2, s[66:67] offset:1024
	global_load_dwordx4 v[126:129], v2, s[66:67] offset:2048
	global_load_dwordx4 v[114:117], v2, s[66:67] offset:3072
	s_mov_b32 s69, 0
	s_mov_b32 s93, 0
	s_min_u32 s14, s69, 63
	s_nop 3
	v_readlane_b32 s30, v26, s14
	v_readlane_b32 s31, v27, s14
	v_bfe_u32 v28, s31, v18, 6
	v_lshl_add_u32 v29, s99, 6, v28
	v_mad_u32_u24 v29, v29, s47, v20
	global_load_dwordx4 v[4:7], v29, s[20:21]
	global_load_dwordx4 v[8:11], v29, s[20:21] offset:32
	global_load_dwordx4 v[12:15], v29, s[20:21] offset:64
	global_load_dwordx4 v[98:101], v29, s[20:21] offset:96
	s_mov_b32 s69, 0
	s_min_u32 s14, s69, 63
	s_nop 3
	v_readlane_b32 s30, v33, s14
	s_and_b32 s30, s30, 0xff
	s_lshl_b32 s30, s30, 13
	s_or_b32 s30, s30, 0x1000
	s_add_u32 s64, s11, s30
	s_addc_u32 s65, s12, 0
	s_add_u32 s66, s8, s30
	s_addc_u32 s67, s9, 0
	global_load_dwordx4 v[162:165], v2, s[64:65]
	global_load_dwordx4 v[154:157], v2, s[64:65] offset:1024
	global_load_dwordx4 v[150:153], v2, s[64:65] offset:2048
	global_load_dwordx4 v[158:161], v2, s[64:65] offset:3072
	global_load_dwordx4 v[138:141], v2, s[66:67]
	global_load_dwordx4 v[122:125], v2, s[66:67] offset:1024
	global_load_dwordx4 v[110:113], v2, s[66:67] offset:2048
	global_load_dwordx4 v[106:109], v2, s[66:67] offset:3072
	s_mov_b32 s69, 1
	s_min_u32 s14, s69, 63
	s_nop 3
	v_readlane_b32 s30, v33, s14
	s_and_b32 s30, s30, 0xff
	s_lshl_b32 s30, s30, 13
	s_add_u32 s64, s11, s30
	s_addc_u32 s65, s12, 0
	s_add_u32 s66, s8, s30
	s_addc_u32 s67, s9, 0
	global_load_dwordx4 v[194:197], v2, s[64:65]
	global_load_dwordx4 v[190:193], v2, s[64:65] offset:1024
	global_load_dwordx4 v[186:189], v2, s[64:65] offset:2048
	global_load_dwordx4 v[182:185], v2, s[64:65] offset:3072
	global_load_dwordx4 v[134:137], v2, s[66:67]
	global_load_dwordx4 v[130:133], v2, s[66:67] offset:1024
	global_load_dwordx4 v[118:121], v2, s[66:67] offset:2048
	global_load_dwordx4 v[102:105], v2, s[66:67] offset:3072

.Lq_tk_k0:
	s_cmp_eq_u32 s93, 0
	s_cbranch_scc0 .Lq_tkp_k0p1

.Lq_wd_k0p0:
	v_bfe_u32 v28, s57, v18, 6
	v_lshl_add_u32 v218, s99, 6, v28
	v_mad_u32_u24 v21, v28, s82, v19
	v_mad_u32_u24 v32, v28, s82, v31
	v_and_b32_e32 v29, s18, v23
	v_cmp_ne_u32_e64 s[54:55], 0, v29
	s_and_b64 s[54:55], s[54:55], s[94:95]
	s_min_u32 s14, s85, 63
	s_nop 3
	v_readlane_b32 s30, v26, s14
	v_readlane_b32 s31, v27, s14
	v_bfe_u32 v28, s31, v18, 6
	v_lshl_add_u32 v29, s99, 6, v28
	v_mad_u32_u24 v29, v29, s47, v20
	global_load_dwordx4 v[238:241], v29, s[20:21]
	global_load_dwordx4 v[242:245], v29, s[20:21] offset:32
	global_load_dwordx4 v[246:249], v29, s[20:21] offset:64
	global_load_dwordx4 v[250:253], v29, s[20:21] offset:96
	s_lshl_b32 s0, s100, 6
	v_or_b32_e32 v237, s0, v206
	v_mov_b32_e32 v221, 0
	s_cmp_lg_u32 s100, s99
	s_cbranch_scc1 .Lq_s0n_k0p0
	v_and_b32_e32 v82, s18, v23
	v_cmp_ne_u32_e32 vcc, 0, v82
	s_and_b64 vcc, s[94:95], vcc
	v_mov_b32 v83, 0
	v_or_b32_e32 v16, 2, v237
	v_cndmask_b32_e32 v82, v236, v222, vcc
	v_sub_f32_e32 v82, v83, v82
	v_mov_b32_e32 v83, v82
	v_mov_b32_e32 v84, v82
	v_mov_b32_e32 v85, v82
	v_mov_b32_e32 v86, v82
	v_mov_b32_e32 v87, v82
	v_mov_b32_e32 v88, v82
	v_mov_b32_e32 v89, v82
	v_mov_b32_e32 v90, v82
	v_mov_b32_e32 v91, v82
	v_mov_b32_e32 v92, v82
	v_mov_b32_e32 v93, v82
	v_mov_b32_e32 v94, v82
	v_mov_b32_e32 v95, v82
	v_mov_b32_e32 v96, v82
	v_mov_b32_e32 v97, v82
	v_cmp_le_i32_e32 vcc, v237, v218
	v_or_b32_e32 v17, 3, v237
	v_mfma_f32_32x32x16_bf16 v[82:97], v[178:181], v[4:7], v[82:97]
	v_or_b32_e32 v30, 8, v237
	v_mfma_f32_32x32x16_bf16 v[82:97], v[174:177], v[8:11], v[82:97]
	v_mfma_f32_32x32x16_bf16 v[82:97], v[170:173], v[12:15], v[82:97]
	v_mfma_f32_32x32x16_bf16 v[82:97], v[166:169], v[98:101], v[82:97]
	s_nop 11
	v_exp_f32_e32 v82, v82
	v_exp_f32_e32 v83, v83
	v_exp_f32_e32 v84, v84
	v_exp_f32_e32 v85, v85
	v_exp_f32_e32 v86, v86
	v_cndmask_b32_e32 v82, 0, v82, vcc
	v_cmp_lt_i32_e32 vcc, v237, v218
	v_exp_f32_e32 v87, v87
	v_exp_f32_e32 v88, v88
	v_cndmask_b32_e32 v83, 0, v83, vcc
	v_cmp_le_i32_e32 vcc, v16, v218
	v_or_b32_e32 v16, 9, v237
	v_exp_f32_e32 v89, v89
	v_cndmask_b32_e32 v84, 0, v84, vcc
	v_cmp_le_i32_e32 vcc, v17, v218
	v_exp_f32_e32 v90, v90
	v_exp_f32_e32 v91, v91
	v_cndmask_b32_e32 v85, 0, v85, vcc
	v_cmp_le_i32_e32 vcc, v30, v218
	v_add_f32_e32 v221, v221, v82
	v_exp_f32_e32 v92, v92
	v_cndmask_b32_e32 v86, 0, v86, vcc
	v_cmp_le_i32_e32 vcc, v16, v218
	v_or_b32_e32 v16, 10, v237
	v_add_f32_e32 v221, v83, v221
	v_cndmask_b32_e32 v87, 0, v87, vcc
	v_cmp_le_i32_e32 vcc, v16, v218
	v_or_b32_e32 v16, 11, v237
	v_exp_f32_e32 v93, v93
	v_cndmask_b32_e32 v88, 0, v88, vcc
	v_cmp_le_i32_e32 vcc, v16, v218
	v_or_b32_e32 v16, 16, v237
	v_add_f32_e32 v221, v84, v221
	v_cndmask_b32_e32 v89, 0, v89, vcc
	v_cmp_le_i32_e32 vcc, v16, v218
	v_or_b32_e32 v16, 17, v237
	v_exp_f32_e32 v94, v94
	v_cndmask_b32_e32 v90, 0, v90, vcc
	v_cmp_le_i32_e32 vcc, v16, v218
	v_or_b32_e32 v16, 18, v237
	v_add_f32_e32 v221, v85, v221
	v_cndmask_b32_e32 v91, 0, v91, vcc
	v_cmp_le_i32_e32 vcc, v16, v218
	v_or_b32_e32 v16, 19, v237
	v_exp_f32_e32 v95, v95
	v_add_f32_e32 v221, v86, v221
	v_cndmask_b32_e32 v92, 0, v92, vcc
	v_cmp_le_i32_e32 vcc, v16, v218
	v_or_b32_e32 v16, 24, v237
	v_cvt_pk_bf16_f32 v82, v82, v83
	v_cvt_pk_bf16_f32 v83, v84, v85
	v_cvt_pk_bf16_f32 v84, v86, v87
	v_cvt_pk_bf16_f32 v85, v88, v89
	v_add_f32_e32 v221, v87, v221
	v_cndmask_b32_e32 v93, 0, v93, vcc
	v_cmp_le_i32_e32 vcc, v16, v218
	v_or_b32_e32 v16, 25, v237
	v_mfma_f32_32x32x16_bf16 v[66:81], v[146:149], v[82:85], 0
	v_add_f32_e32 v221, v88, v221
	v_cndmask_b32_e32 v94, 0, v94, vcc
	v_exp_f32_e32 v86, v96
	v_cmp_le_i32_e32 vcc, v16, v218
	v_or_b32_e32 v88, 26, v237
	v_add_f32_e32 v221, v89, v221
	v_cndmask_b32_e32 v87, 0, v95, vcc
	v_mfma_f32_32x32x16_bf16 v[50:65], v[142:145], v[82:85], 0
	v_cmp_le_i32_e32 vcc, v88, v218
	v_exp_f32_e32 v88, v97
	v_or_b32_e32 v82, 27, v237
	v_cndmask_b32_e32 v86, 0, v86, vcc
	v_cmp_le_i32_e32 vcc, v82, v218
	v_cvt_pk_bf16_f32 v82, v90, v91
	v_cvt_pk_bf16_f32 v83, v92, v93
	v_cndmask_b32_e32 v88, 0, v88, vcc
	v_cvt_pk_bf16_f32 v84, v94, v87
	v_cvt_pk_bf16_f32 v85, v86, v88
	v_add_f32_e32 v221, v90, v221
	v_add_f32_e32 v89, v91, v221
	v_mfma_f32_32x32x16_bf16 v[66:81], v[126:129], v[82:85], v[66:81]
	v_add_f32_e32 v89, v92, v89
	v_add_f32_e32 v89, v93, v89
	v_add_f32_e32 v89, v94, v89
	v_add_f32_e32 v87, v87, v89
	v_add_f32_e32 v86, v86, v87
	v_add_f32_e32 v221, v88, v86
	v_mfma_f32_32x32x16_bf16 v[50:65], v[114:117], v[82:85], v[50:65]
	s_cmp_lg_u32 s85, s86
	s_cbranch_scc1 .Lq_nl0_k0p0
	s_min_u32 s14, s87, 63
	s_nop 3
	v_readlane_b32 s30, v33, s14
	s_and_b32 s30, s30, 0xff
	s_lshl_b32 s30, s30, 13
	s_or_b32 s30, s30, 0x1000
	s_add_u32 s64, s11, s30
	s_addc_u32 s65, s12, 0
	s_add_u32 s66, s8, s30
	s_addc_u32 s67, s9, 0
	global_load_dwordx4 v[178:181], v2, s[64:65]
	global_load_dwordx4 v[174:177], v2, s[64:65] offset:1024
	global_load_dwordx4 v[170:173], v2, s[64:65] offset:2048
	global_load_dwordx4 v[166:169], v2, s[64:65] offset:3072
	global_load_dwordx4 v[146:149], v2, s[66:67]
	global_load_dwordx4 v[142:145], v2, s[66:67] offset:1024
	global_load_dwordx4 v[126:129], v2, s[66:67] offset:2048
	global_load_dwordx4 v[114:117], v2, s[66:67] offset:3072
	s_waitcnt vmcnt(20)
	s_branch .Lq_nl0d_k0p0

.Lq_locked_k0p0:
	s_mov_b64 exec, s[54:55]
	ds_read_b128 v[82:85], v21
	ds_read_b128 v[86:89], v21 offset:32
	ds_read_b128 v[90:93], v21 offset:64
	ds_read_b128 v[94:97], v21 offset:96
	ds_read_b128 v[34:37], v21 offset:128
	ds_read_b128 v[38:41], v21 offset:160
	ds_read_b128 v[42:45], v21 offset:192
	ds_read_b128 v[46:49], v21 offset:224
	ds_read_b32 v28, v32
	s_waitcnt lgkmcnt(0)
	v_add_f32_e32 v82, v82, v66
	v_add_f32_e32 v83, v83, v67
	v_add_f32_e32 v84, v84, v68
	v_add_f32_e32 v85, v85, v69
	v_add_f32_e32 v86, v86, v70
	v_add_f32_e32 v87, v87, v71
	v_add_f32_e32 v88, v88, v72
	v_add_f32_e32 v89, v89, v73
	v_add_f32_e32 v90, v90, v74
	v_add_f32_e32 v91, v91, v75
	v_add_f32_e32 v92, v92, v76
	v_add_f32_e32 v93, v93, v77
	v_add_f32_e32 v94, v94, v78
	v_add_f32_e32 v95, v95, v79
	v_add_f32_e32 v96, v96, v80
	v_add_f32_e32 v97, v97, v81
	v_add_f32_e32 v34, v34, v50
	v_add_f32_e32 v35, v35, v51
	v_add_f32_e32 v36, v36, v52
	v_add_f32_e32 v37, v37, v53
	v_add_f32_e32 v38, v38, v54
	v_add_f32_e32 v39, v39, v55
	v_add_f32_e32 v40, v40, v56
	v_add_f32_e32 v41, v41, v57
	v_add_f32_e32 v42, v42, v58
	v_add_f32_e32 v43, v43, v59
	v_add_f32_e32 v44, v44, v60
	v_add_f32_e32 v45, v45, v61
	v_add_f32_e32 v46, v46, v62
	v_add_f32_e32 v47, v47, v63
	v_add_f32_e32 v48, v48, v64
	v_add_f32_e32 v49, v49, v65
	v_add_f32_e32 v28, v28, v221
	ds_write_b128 v21, v[82:85]
	ds_write_b128 v21, v[86:89] offset:32
	ds_write_b128 v21, v[90:93] offset:64
	ds_write_b128 v21, v[94:97] offset:96
	ds_write_b128 v21, v[34:37] offset:128
	ds_write_b128 v21, v[38:41] offset:160
	ds_write_b128 v21, v[42:45] offset:192
	ds_write_b128 v21, v[46:49] offset:224
	ds_write_b32 v32, v28
	s_mov_b64 exec, 1
	s_not_b64 s[64:65], s[60:61]
	v_mov_b32_e32 v16, s64
	v_mov_b32_e32 v17, s65
	ds_and_b64 v30, v[16:17]
	s_mov_b64 exec, s[58:59]
	s_xor_b32 s93, s93, 1
	s_mov_b32 s68, s85
	s_cmp_lt_u32 s68, s86
	s_cbranch_scc1 .Lq_tk_k0
	s_branch .Lq_vend_k0

.Lq_wd_k0p1:
	v_bfe_u32 v28, s57, v18, 6
	v_lshl_add_u32 v218, s99, 6, v28
	v_mad_u32_u24 v21, v28, s82, v19
	v_mad_u32_u24 v32, v28, s82, v31
	v_and_b32_e32 v29, s18, v23
	v_cmp_ne_u32_e64 s[54:55], 0, v29
	s_and_b64 s[54:55], s[54:55], s[94:95]
	s_min_u32 s14, s85, 63
	s_nop 3
	v_readlane_b32 s30, v26, s14
	v_readlane_b32 s31, v27, s14
	v_bfe_u32 v28, s31, v18, 6
	v_lshl_add_u32 v29, s99, 6, v28
	v_mad_u32_u24 v29, v29, s47, v20
	global_load_dwordx4 v[4:7], v29, s[20:21]
	global_load_dwordx4 v[8:11], v29, s[20:21] offset:32
	global_load_dwordx4 v[12:15], v29, s[20:21] offset:64
	global_load_dwordx4 v[98:101], v29, s[20:21] offset:96
	s_lshl_b32 s0, s100, 6
	v_or_b32_e32 v237, s0, v206
	v_mov_b32_e32 v221, 0
	s_cmp_lg_u32 s100, s99
	s_cbranch_scc1 .Lq_s0n_k0p1
	v_and_b32_e32 v82, s18, v23
	v_cmp_ne_u32_e32 vcc, 0, v82
	s_and_b64 vcc, s[94:95], vcc
	v_mov_b32 v83, 0
	v_or_b32_e32 v16, 2, v237
	v_cndmask_b32_e32 v82, v236, v222, vcc
	v_sub_f32_e32 v82, v83, v82
	v_mov_b32_e32 v83, v82
	v_mov_b32_e32 v84, v82
	v_mov_b32_e32 v85, v82
	v_mov_b32_e32 v86, v82
	v_mov_b32_e32 v87, v82
	v_mov_b32_e32 v88, v82
	v_mov_b32_e32 v89, v82
	v_mov_b32_e32 v90, v82
	v_mov_b32_e32 v91, v82
	v_mov_b32_e32 v92, v82
	v_mov_b32_e32 v93, v82
	v_mov_b32_e32 v94, v82
	v_mov_b32_e32 v95, v82
	v_mov_b32_e32 v96, v82
	v_mov_b32_e32 v97, v82
	v_cmp_le_i32_e32 vcc, v237, v218
	v_or_b32_e32 v17, 3, v237
	v_mfma_f32_32x32x16_bf16 v[82:97], v[178:181], v[238:241], v[82:97]
	v_or_b32_e32 v30, 8, v237
	v_mfma_f32_32x32x16_bf16 v[82:97], v[174:177], v[242:245], v[82:97]
	v_mfma_f32_32x32x16_bf16 v[82:97], v[170:173], v[246:249], v[82:97]
	v_mfma_f32_32x32x16_bf16 v[82:97], v[166:169], v[250:253], v[82:97]
	s_nop 11
	v_exp_f32_e32 v82, v82
	v_exp_f32_e32 v83, v83
	v_exp_f32_e32 v84, v84
	v_exp_f32_e32 v85, v85
	v_exp_f32_e32 v86, v86
	v_cndmask_b32_e32 v82, 0, v82, vcc
	v_cmp_lt_i32_e32 vcc, v237, v218
	v_exp_f32_e32 v87, v87
	v_exp_f32_e32 v88, v88
	v_cndmask_b32_e32 v83, 0, v83, vcc
	v_cmp_le_i32_e32 vcc, v16, v218
	v_or_b32_e32 v16, 9, v237
	v_exp_f32_e32 v89, v89
	v_cndmask_b32_e32 v84, 0, v84, vcc
	v_cmp_le_i32_e32 vcc, v17, v218
	v_exp_f32_e32 v90, v90
	v_exp_f32_e32 v91, v91
	v_cndmask_b32_e32 v85, 0, v85, vcc
	v_cmp_le_i32_e32 vcc, v30, v218
	v_add_f32_e32 v221, v221, v82
	v_exp_f32_e32 v92, v92
	v_cndmask_b32_e32 v86, 0, v86, vcc
	v_cmp_le_i32_e32 vcc, v16, v218
	v_or_b32_e32 v16, 10, v237
	v_add_f32_e32 v221, v83, v221
	v_cndmask_b32_e32 v87, 0, v87, vcc
	v_cmp_le_i32_e32 vcc, v16, v218
	v_or_b32_e32 v16, 11, v237
	v_exp_f32_e32 v93, v93
	v_cndmask_b32_e32 v88, 0, v88, vcc
	v_cmp_le_i32_e32 vcc, v16, v218
	v_or_b32_e32 v16, 16, v237
	v_add_f32_e32 v221, v84, v221
	v_cndmask_b32_e32 v89, 0, v89, vcc
	v_cmp_le_i32_e32 vcc, v16, v218
	v_or_b32_e32 v16, 17, v237
	v_exp_f32_e32 v94, v94
	v_cndmask_b32_e32 v90, 0, v90, vcc
	v_cmp_le_i32_e32 vcc, v16, v218
	v_or_b32_e32 v16, 18, v237
	v_add_f32_e32 v221, v85, v221
	v_cndmask_b32_e32 v91, 0, v91, vcc
	v_cmp_le_i32_e32 vcc, v16, v218
	v_or_b32_e32 v16, 19, v237
	v_exp_f32_e32 v95, v95
	v_add_f32_e32 v221, v86, v221
	v_cndmask_b32_e32 v92, 0, v92, vcc
	v_cmp_le_i32_e32 vcc, v16, v218
	v_or_b32_e32 v16, 24, v237
	v_cvt_pk_bf16_f32 v82, v82, v83
	v_cvt_pk_bf16_f32 v83, v84, v85
	v_cvt_pk_bf16_f32 v84, v86, v87
	v_cvt_pk_bf16_f32 v85, v88, v89
	v_add_f32_e32 v221, v87, v221
	v_cndmask_b32_e32 v93, 0, v93, vcc
	v_cmp_le_i32_e32 vcc, v16, v218
	v_or_b32_e32 v16, 25, v237
	v_mfma_f32_32x32x16_bf16 v[66:81], v[146:149], v[82:85], 0
	v_add_f32_e32 v221, v88, v221
	v_cndmask_b32_e32 v94, 0, v94, vcc
	v_exp_f32_e32 v86, v96
	v_cmp_le_i32_e32 vcc, v16, v218
	v_or_b32_e32 v88, 26, v237
	v_add_f32_e32 v221, v89, v221
	v_cndmask_b32_e32 v87, 0, v95, vcc
	v_mfma_f32_32x32x16_bf16 v[50:65], v[142:145], v[82:85], 0
	v_cmp_le_i32_e32 vcc, v88, v218
	v_exp_f32_e32 v88, v97
	v_or_b32_e32 v82, 27, v237
	v_cndmask_b32_e32 v86, 0, v86, vcc
	v_cmp_le_i32_e32 vcc, v82, v218
	v_cvt_pk_bf16_f32 v82, v90, v91
	v_cvt_pk_bf16_f32 v83, v92, v93
	v_cndmask_b32_e32 v88, 0, v88, vcc
	v_cvt_pk_bf16_f32 v84, v94, v87
	v_cvt_pk_bf16_f32 v85, v86, v88
	v_add_f32_e32 v221, v90, v221
	v_add_f32_e32 v89, v91, v221
	v_mfma_f32_32x32x16_bf16 v[66:81], v[126:129], v[82:85], v[66:81]
	v_add_f32_e32 v89, v92, v89
	v_add_f32_e32 v89, v93, v89
	v_add_f32_e32 v89, v94, v89
	v_add_f32_e32 v87, v87, v89
	v_add_f32_e32 v86, v86, v87
	v_add_f32_e32 v221, v88, v86
	v_mfma_f32_32x32x16_bf16 v[50:65], v[114:117], v[82:85], v[50:65]
	s_cmp_lg_u32 s85, s86
	s_cbranch_scc1 .Lq_nl0_k0p1
	s_min_u32 s14, s87, 63
	s_nop 3
	v_readlane_b32 s30, v33, s14
	s_and_b32 s30, s30, 0xff
	s_lshl_b32 s30, s30, 13
	s_or_b32 s30, s30, 0x1000
	s_add_u32 s64, s11, s30
	s_addc_u32 s65, s12, 0
	s_add_u32 s66, s8, s30
	s_addc_u32 s67, s9, 0
	global_load_dwordx4 v[178:181], v2, s[64:65]
	global_load_dwordx4 v[174:177], v2, s[64:65] offset:1024
	global_load_dwordx4 v[170:173], v2, s[64:65] offset:2048
	global_load_dwordx4 v[166:169], v2, s[64:65] offset:3072
	global_load_dwordx4 v[146:149], v2, s[66:67]
	global_load_dwordx4 v[142:145], v2, s[66:67] offset:1024
	global_load_dwordx4 v[126:129], v2, s[66:67] offset:2048
	global_load_dwordx4 v[114:117], v2, s[66:67] offset:3072
	s_waitcnt vmcnt(20)
	s_branch .Lq_nl0d_k0p1

.Lq_nl0d_k0p1:
	s_lshl_b32 s0, s100, 6
	s_or_b32 s0, s0, 32
	v_or_b32_e32 v237, s0, v206
	v_and_b32_e32 v82, s18, v23
	v_cmp_ne_u32_e32 vcc, 0, v82
	s_and_b64 vcc, s[94:95], vcc
	v_mov_b32 v83, 0
	v_or_b32_e32 v16, 2, v237
	v_cndmask_b32_e32 v82, v236, v222, vcc
	v_sub_f32_e32 v82, v83, v82
	v_mov_b32_e32 v83, v82
	v_mov_b32_e32 v84, v82
	v_mov_b32_e32 v85, v82
	v_mov_b32_e32 v86, v82
	v_mov_b32_e32 v87, v82
	v_mov_b32_e32 v88, v82
	v_mov_b32_e32 v89, v82
	v_mov_b32_e32 v90, v82
	v_mov_b32_e32 v91, v82
	v_mov_b32_e32 v92, v82
	v_mov_b32_e32 v93, v82
	v_mov_b32_e32 v94, v82
	v_mov_b32_e32 v95, v82
	v_mov_b32_e32 v96, v82
	v_mov_b32_e32 v97, v82
	v_cmp_le_i32_e32 vcc, v237, v218
	v_or_b32_e32 v17, 3, v237
	v_mfma_f32_32x32x16_bf16 v[82:97], v[162:165], v[238:241], v[82:97]
	v_or_b32_e32 v30, 8, v237
	v_mfma_f32_32x32x16_bf16 v[82:97], v[154:157], v[242:245], v[82:97]
	v_mfma_f32_32x32x16_bf16 v[82:97], v[150:153], v[246:249], v[82:97]
	v_mfma_f32_32x32x16_bf16 v[82:97], v[158:161], v[250:253], v[82:97]
	s_nop 11
	v_exp_f32_e32 v82, v82
	v_exp_f32_e32 v83, v83
	v_exp_f32_e32 v84, v84
	v_exp_f32_e32 v85, v85
	v_exp_f32_e32 v86, v86
	v_cndmask_b32_e32 v82, 0, v82, vcc
	v_cmp_lt_i32_e32 vcc, v237, v218
	v_exp_f32_e32 v87, v87
	v_exp_f32_e32 v88, v88
	v_cndmask_b32_e32 v83, 0, v83, vcc
	v_cmp_le_i32_e32 vcc, v16, v218
	v_or_b32_e32 v16, 9, v237
	v_exp_f32_e32 v89, v89
	v_cndmask_b32_e32 v84, 0, v84, vcc
	v_cmp_le_i32_e32 vcc, v17, v218
	v_exp_f32_e32 v90, v90
	v_exp_f32_e32 v91, v91
	v_cndmask_b32_e32 v85, 0, v85, vcc
	v_cmp_le_i32_e32 vcc, v30, v218
	v_add_f32_e32 v221, v221, v82
	v_exp_f32_e32 v92, v92
	v_cndmask_b32_e32 v86, 0, v86, vcc
	v_cmp_le_i32_e32 vcc, v16, v218
	v_or_b32_e32 v16, 10, v237
	v_add_f32_e32 v221, v83, v221
	v_cndmask_b32_e32 v87, 0, v87, vcc
	v_cmp_le_i32_e32 vcc, v16, v218
	v_or_b32_e32 v16, 11, v237
	v_exp_f32_e32 v93, v93
	v_cndmask_b32_e32 v88, 0, v88, vcc
	v_cmp_le_i32_e32 vcc, v16, v218
	v_or_b32_e32 v16, 16, v237
	v_add_f32_e32 v221, v84, v221
	v_cndmask_b32_e32 v89, 0, v89, vcc
	v_cmp_le_i32_e32 vcc, v16, v218
	v_or_b32_e32 v16, 17, v237
	v_exp_f32_e32 v94, v94
	v_cndmask_b32_e32 v90, 0, v90, vcc
	v_cmp_le_i32_e32 vcc, v16, v218
	v_or_b32_e32 v16, 18, v237
	v_add_f32_e32 v221, v85, v221
	v_cndmask_b32_e32 v91, 0, v91, vcc
	v_cmp_le_i32_e32 vcc, v16, v218
	v_or_b32_e32 v16, 19, v237
	v_exp_f32_e32 v95, v95
	v_add_f32_e32 v221, v86, v221
	v_cndmask_b32_e32 v92, 0, v92, vcc
	v_cmp_le_i32_e32 vcc, v16, v218
	v_or_b32_e32 v16, 24, v237
	v_cvt_pk_bf16_f32 v82, v82, v83
	v_cvt_pk_bf16_f32 v83, v84, v85
	v_cvt_pk_bf16_f32 v84, v86, v87
	v_cvt_pk_bf16_f32 v85, v88, v89
	v_add_f32_e32 v221, v87, v221
	v_cndmask_b32_e32 v93, 0, v93, vcc
	v_cmp_le_i32_e32 vcc, v16, v218
	v_or_b32_e32 v16, 25, v237
	v_mfma_f32_32x32x16_bf16 v[66:81], v[138:141], v[82:85], v[66:81]
	v_add_f32_e32 v221, v88, v221
	v_cndmask_b32_e32 v94, 0, v94, vcc
	v_exp_f32_e32 v86, v96
	v_cmp_le_i32_e32 vcc, v16, v218
	v_or_b32_e32 v88, 26, v237
	v_add_f32_e32 v221, v89, v221
	v_cndmask_b32_e32 v87, 0, v95, vcc
	v_mfma_f32_32x32x16_bf16 v[50:65], v[122:125], v[82:85], v[50:65]
	v_cmp_le_i32_e32 vcc, v88, v218
	v_exp_f32_e32 v88, v97
	v_or_b32_e32 v82, 27, v237
	v_cndmask_b32_e32 v86, 0, v86, vcc
	v_cmp_le_i32_e32 vcc, v82, v218
	v_cvt_pk_bf16_f32 v82, v90, v91
	v_cvt_pk_bf16_f32 v83, v92, v93
	v_cndmask_b32_e32 v88, 0, v88, vcc
	v_cvt_pk_bf16_f32 v84, v94, v87
	v_cvt_pk_bf16_f32 v85, v86, v88
	v_add_f32_e32 v221, v90, v221
	v_add_f32_e32 v89, v91, v221
	v_mfma_f32_32x32x16_bf16 v[66:81], v[110:113], v[82:85], v[66:81]
	v_add_f32_e32 v89, v92, v89
	v_add_f32_e32 v89, v93, v89
	v_add_f32_e32 v89, v94, v89
	v_add_f32_e32 v87, v87, v89
	v_add_f32_e32 v86, v86, v87
	v_add_f32_e32 v221, v88, v86
	v_mfma_f32_32x32x16_bf16 v[50:65], v[106:109], v[82:85], v[50:65]
	s_cmp_lg_u32 s85, s86
	s_cbranch_scc1 .Lq_nl1_k0p1
	s_min_u32 s14, s88, 63
	s_nop 3
	v_readlane_b32 s30, v33, s14
	s_and_b32 s30, s30, 0xff
	s_lshl_b32 s30, s30, 13
	s_add_u32 s64, s11, s30
	s_addc_u32 s65, s12, 0
	s_add_u32 s66, s8, s30
	s_addc_u32 s67, s9, 0
	global_load_dwordx4 v[162:165], v2, s[64:65]
	global_load_dwordx4 v[154:157], v2, s[64:65] offset:1024
	global_load_dwordx4 v[150:153], v2, s[64:65] offset:2048
	global_load_dwordx4 v[158:161], v2, s[64:65] offset:3072
	global_load_dwordx4 v[138:141], v2, s[66:67]
	global_load_dwordx4 v[122:125], v2, s[66:67] offset:1024
	global_load_dwordx4 v[110:113], v2, s[66:67] offset:2048
	global_load_dwordx4 v[106:109], v2, s[66:67] offset:3072
	s_branch .Lq_nl1_k0p1
.Lq_s0n_k0p1:
	v_and_b32_e32 v82, s18, v23
	v_cmp_ne_u32_e32 vcc, 0, v82
	s_and_b64 vcc, s[94:95], vcc
	v_mov_b32 v83, 0
	v_cndmask_b32_e32 v82, v236, v222, vcc
	v_sub_f32_e32 v82, v83, v82
	v_mov_b32_e32 v83, v82
	v_mov_b32_e32 v84, v82
	v_mov_b32_e32 v85, v82
	v_mov_b32_e32 v86, v82
	v_mov_b32_e32 v87, v82
	v_mov_b32_e32 v88, v82
	v_mov_b32_e32 v89, v82
	v_mov_b32_e32 v90, v82
	v_mov_b32_e32 v91, v82
	v_mov_b32_e32 v92, v82
	v_mov_b32_e32 v93, v82
	v_mov_b32_e32 v94, v82
	v_mov_b32_e32 v95, v82
	v_mov_b32_e32 v96, v82
	v_mov_b32_e32 v97, v82
	s_nop 1
	v_mfma_f32_32x32x16_bf16 v[82:97], v[178:181], v[238:241], v[82:97]
	v_mfma_f32_32x32x16_bf16 v[82:97], v[174:177], v[242:245], v[82:97]
	v_mfma_f32_32x32x16_bf16 v[82:97], v[170:173], v[246:249], v[82:97]
	v_mfma_f32_32x32x16_bf16 v[82:97], v[166:169], v[250:253], v[82:97]
	s_waitcnt vmcnt(12)
	v_mov_b32_e32 v28, 0
	v_and_b32_e32 v34, s18, v23
	v_cmp_ne_u32_e32 vcc, 0, v34
	s_and_b64 vcc, s[94:95], vcc
	v_mov_b32 v35, 0
	v_cndmask_b32_e32 v34, v236, v222, vcc
	v_sub_f32_e32 v34, v35, v34
	v_mov_b32_e32 v35, v34
	v_mov_b32_e32 v36, v34
	v_mov_b32_e32 v37, v34
	v_mov_b32_e32 v38, v34
	v_mov_b32_e32 v39, v34
	v_mov_b32_e32 v40, v34
	v_mov_b32_e32 v41, v34
	v_mov_b32_e32 v42, v34
	v_mov_b32_e32 v43, v34
	v_mov_b32_e32 v44, v34
	v_mov_b32_e32 v45, v34
	v_mov_b32_e32 v46, v34
	v_mov_b32_e32 v47, v34
	v_mov_b32_e32 v48, v34
	v_mov_b32_e32 v49, v34
	s_nop 1
	v_mfma_f32_32x32x16_bf16 v[34:49], v[162:165], v[238:241], v[34:49]
	v_mfma_f32_32x32x16_bf16 v[34:49], v[154:157], v[242:245], v[34:49]
	v_mfma_f32_32x32x16_bf16 v[34:49], v[150:153], v[246:249], v[34:49]
	v_mfma_f32_32x32x16_bf16 v[34:49], v[158:161], v[250:253], v[34:49]
	v_exp_f32_e32 v82, v82
	v_exp_f32_e32 v83, v83
	v_exp_f32_e32 v84, v84
	v_exp_f32_e32 v85, v85
	v_exp_f32_e32 v86, v86
	v_exp_f32_e32 v87, v87
	v_exp_f32_e32 v88, v88
	v_exp_f32_e32 v89, v89
	v_exp_f32_e32 v90, v90
	v_exp_f32_e32 v91, v91
	v_add_f32_e32 v221, v221, v82
	v_exp_f32_e32 v92, v92
	v_exp_f32_e32 v34, v34
	v_add_f32_e32 v221, v83, v221
	v_exp_f32_e32 v35, v35
	v_exp_f32_e32 v93, v93
	v_exp_f32_e32 v36, v36
	v_add_f32_e32 v221, v84, v221
	v_exp_f32_e32 v37, v37
	v_exp_f32_e32 v94, v94
	v_exp_f32_e32 v38, v38
	v_add_f32_e32 v221, v85, v221
	v_exp_f32_e32 v39, v39
	v_exp_f32_e32 v95, v95
	v_exp_f32_e32 v40, v40
	v_add_f32_e32 v221, v86, v221
	v_exp_f32_e32 v41, v41
	v_cvt_pk_bf16_f32 v82, v82, v83
	v_exp_f32_e32 v42, v42
	v_cvt_pk_bf16_f32 v83, v84, v85
	v_exp_f32_e32 v43, v43
	v_cvt_pk_bf16_f32 v84, v86, v87
	v_add_f32_e32 v28, v28, v34
	v_cvt_pk_bf16_f32 v85, v88, v89
	v_exp_f32_e32 v44, v44
	v_add_f32_e32 v221, v87, v221
	v_add_f32_e32 v28, v35, v28
	v_mfma_f32_32x32x16_bf16 v[66:81], v[146:149], v[82:85], 0
	v_exp_f32_e32 v45, v45
	v_add_f32_e32 v221, v88, v221
	v_add_f32_e32 v28, v36, v28
	v_exp_f32_e32 v86, v96
	v_exp_f32_e32 v46, v46
	v_add_f32_e32 v221, v89, v221
	v_add_f32_e32 v28, v37, v28
	v_mov_b32_e32 v87, v95
	v_exp_f32_e32 v47, v47
	v_mfma_f32_32x32x16_bf16 v[50:65], v[142:145], v[82:85], 0
	v_add_f32_e32 v28, v38, v28
	v_exp_f32_e32 v88, v97
	v_cvt_pk_bf16_f32 v34, v34, v35
	v_cvt_pk_bf16_f32 v82, v90, v91
	v_cvt_pk_bf16_f32 v35, v36, v37
	v_cvt_pk_bf16_f32 v83, v92, v93
	v_cvt_pk_bf16_f32 v36, v38, v39
	v_cvt_pk_bf16_f32 v84, v94, v87
	v_cvt_pk_bf16_f32 v37, v40, v41
	v_cvt_pk_bf16_f32 v85, v86, v88
	v_add_f32_e32 v28, v39, v28
	v_add_f32_e32 v221, v90, v221
	v_mfma_f32_32x32x16_bf16 v[66:81], v[138:141], v[34:37], v[66:81]
	v_add_f32_e32 v89, v91, v221
	v_add_f32_e32 v28, v40, v28
	v_mfma_f32_32x32x16_bf16 v[66:81], v[126:129], v[82:85], v[66:81]
	v_exp_f32_e32 v38, v48
	v_add_f32_e32 v89, v92, v89
	v_add_f32_e32 v28, v41, v28
	v_add_f32_e32 v89, v93, v89
	v_mov_b32_e32 v39, v47
	v_add_f32_e32 v89, v94, v89
	v_mfma_f32_32x32x16_bf16 v[50:65], v[122:125], v[34:37], v[50:65]
	v_add_f32_e32 v87, v87, v89
	v_exp_f32_e32 v40, v49
	v_add_f32_e32 v86, v86, v87
	v_cvt_pk_bf16_f32 v34, v42, v43
	v_add_f32_e32 v221, v88, v86
	v_cvt_pk_bf16_f32 v35, v44, v45
	v_mfma_f32_32x32x16_bf16 v[50:65], v[114:117], v[82:85], v[50:65]
	v_cvt_pk_bf16_f32 v36, v46, v39
	v_cvt_pk_bf16_f32 v37, v38, v40
	v_add_f32_e32 v28, v42, v28
	v_add_f32_e32 v41, v43, v28
	v_mfma_f32_32x32x16_bf16 v[66:81], v[110:113], v[34:37], v[66:81]
	v_add_f32_e32 v41, v44, v41
	v_add_f32_e32 v41, v45, v41
	v_add_f32_e32 v41, v46, v41
	v_add_f32_e32 v39, v39, v41
	v_add_f32_e32 v38, v38, v39
	v_add_f32_e32 v28, v40, v38
	v_mfma_f32_32x32x16_bf16 v[50:65], v[106:109], v[34:37], v[50:65]
	v_add_f32_e32 v221, v221, v28
	s_cmp_lg_u32 s85, s86
	s_cbranch_scc1 .Lq_nl1_k0p1
	s_min_u32 s14, s87, 63
	s_nop 3
	v_readlane_b32 s30, v33, s14
	s_and_b32 s30, s30, 0xff
	s_lshl_b32 s30, s30, 13
	s_or_b32 s30, s30, 0x1000
	s_add_u32 s64, s11, s30
	s_addc_u32 s65, s12, 0
	s_add_u32 s66, s8, s30
	s_addc_u32 s67, s9, 0
	global_load_dwordx4 v[178:181], v2, s[64:65]
	global_load_dwordx4 v[174:177], v2, s[64:65] offset:1024
	global_load_dwordx4 v[170:173], v2, s[64:65] offset:2048
	global_load_dwordx4 v[166:169], v2, s[64:65] offset:3072
	global_load_dwordx4 v[146:149], v2, s[66:67]
	global_load_dwordx4 v[142:145], v2, s[66:67] offset:1024
	global_load_dwordx4 v[126:129], v2, s[66:67] offset:2048
	global_load_dwordx4 v[114:117], v2, s[66:67] offset:3072
	s_min_u32 s14, s88, 63
	s_nop 3
	v_readlane_b32 s30, v33, s14
	s_and_b32 s30, s30, 0xff
	s_lshl_b32 s30, s30, 13
	s_add_u32 s64, s11, s30
	s_addc_u32 s65, s12, 0
	s_add_u32 s66, s8, s30
	s_addc_u32 s67, s9, 0
	global_load_dwordx4 v[162:165], v2, s[64:65]
	global_load_dwordx4 v[154:157], v2, s[64:65] offset:1024
	global_load_dwordx4 v[150:153], v2, s[64:65] offset:2048
	global_load_dwordx4 v[158:161], v2, s[64:65] offset:3072
	global_load_dwordx4 v[138:141], v2, s[66:67]
	global_load_dwordx4 v[122:125], v2, s[66:67] offset:1024
	global_load_dwordx4 v[110:113], v2, s[66:67] offset:2048
	global_load_dwordx4 v[106:109], v2, s[66:67] offset:3072

.Lq_vend_k0:
.Lq_visit_k1:
	s_lshr_b32 s84, s52, 1
	s_add_i32 s84, s84, 1
	s_cmp_ge_u32 s84, s89
	s_cbranch_scc1 .Lq_loop_end
	s_min_u32 s14, s84, 63
	s_nop 3
	v_readlane_b32 s0, v33, s14
	s_and_b32 s100, s0, 0xff
	s_lshr_b32 s68, s0, 8
	s_mov_b32 s91, s68
	s_add_i32 s1, s84, 1
	s_min_u32 s14, s1, 63
	s_nop 3
	v_readlane_b32 s86, v33, s14
	s_lshr_b32 s86, s86, 8
	s_cmp_ge_u32 s1, s89
	s_cselect_b32 s86, s10, s86
	s_add_i32 s87, s84, 1
	s_add_i32 s88, s84, 2

.Lq_wd_k1p0:
	v_bfe_u32 v28, s57, v18, 6
	v_lshl_add_u32 v218, s99, 6, v28
	v_mad_u32_u24 v21, v28, s82, v19
	v_mad_u32_u24 v32, v28, s82, v31
	v_and_b32_e32 v29, s18, v23
	v_cmp_ne_u32_e64 s[54:55], 0, v29
	s_and_b64 s[54:55], s[54:55], s[94:95]
	s_min_u32 s14, s85, 63
	s_nop 3
	v_readlane_b32 s30, v26, s14
	v_readlane_b32 s31, v27, s14
	v_bfe_u32 v28, s31, v18, 6
	v_lshl_add_u32 v29, s99, 6, v28
	v_mad_u32_u24 v29, v29, s47, v20
	global_load_dwordx4 v[238:241], v29, s[20:21]
	global_load_dwordx4 v[242:245], v29, s[20:21] offset:32
	global_load_dwordx4 v[246:249], v29, s[20:21] offset:64
	global_load_dwordx4 v[250:253], v29, s[20:21] offset:96
	s_lshl_b32 s0, s100, 6
	v_or_b32_e32 v237, s0, v206
	v_mov_b32_e32 v221, 0
	s_cmp_lg_u32 s100, s99
	s_cbranch_scc1 .Lq_s0n_k1p0
	v_and_b32_e32 v82, s18, v23
	v_cmp_ne_u32_e32 vcc, 0, v82
	s_and_b64 vcc, s[94:95], vcc
	v_mov_b32 v83, 0
	v_or_b32_e32 v16, 2, v237
	v_cndmask_b32_e32 v82, v236, v222, vcc
	v_sub_f32_e32 v82, v83, v82
	v_mov_b32_e32 v83, v82
	v_mov_b32_e32 v84, v82
	v_mov_b32_e32 v85, v82
	v_mov_b32_e32 v86, v82
	v_mov_b32_e32 v87, v82
	v_mov_b32_e32 v88, v82
	v_mov_b32_e32 v89, v82
	v_mov_b32_e32 v90, v82
	v_mov_b32_e32 v91, v82
	v_mov_b32_e32 v92, v82
	v_mov_b32_e32 v93, v82
	v_mov_b32_e32 v94, v82
	v_mov_b32_e32 v95, v82
	v_mov_b32_e32 v96, v82
	v_mov_b32_e32 v97, v82
	v_cmp_le_i32_e32 vcc, v237, v218
	v_or_b32_e32 v17, 3, v237
	v_mfma_f32_32x32x16_bf16 v[82:97], v[194:197], v[4:7], v[82:97]
	v_or_b32_e32 v30, 8, v237
	v_mfma_f32_32x32x16_bf16 v[82:97], v[190:193], v[8:11], v[82:97]
	v_mfma_f32_32x32x16_bf16 v[82:97], v[186:189], v[12:15], v[82:97]
	v_mfma_f32_32x32x16_bf16 v[82:97], v[182:185], v[98:101], v[82:97]
	s_nop 11
	v_exp_f32_e32 v82, v82
	v_exp_f32_e32 v83, v83
	v_exp_f32_e32 v84, v84
	v_exp_f32_e32 v85, v85
	v_exp_f32_e32 v86, v86
	v_cndmask_b32_e32 v82, 0, v82, vcc
	v_cmp_lt_i32_e32 vcc, v237, v218
	v_exp_f32_e32 v87, v87
	v_exp_f32_e32 v88, v88
	v_cndmask_b32_e32 v83, 0, v83, vcc
	v_cmp_le_i32_e32 vcc, v16, v218
	v_or_b32_e32 v16, 9, v237
	v_exp_f32_e32 v89, v89
	v_cndmask_b32_e32 v84, 0, v84, vcc
	v_cmp_le_i32_e32 vcc, v17, v218
	v_exp_f32_e32 v90, v90
	v_exp_f32_e32 v91, v91
	v_cndmask_b32_e32 v85, 0, v85, vcc
	v_cmp_le_i32_e32 vcc, v30, v218
	v_add_f32_e32 v221, v221, v82
	v_exp_f32_e32 v92, v92
	v_cndmask_b32_e32 v86, 0, v86, vcc
	v_cmp_le_i32_e32 vcc, v16, v218
	v_or_b32_e32 v16, 10, v237
	v_add_f32_e32 v221, v83, v221
	v_cndmask_b32_e32 v87, 0, v87, vcc
	v_cmp_le_i32_e32 vcc, v16, v218
	v_or_b32_e32 v16, 11, v237
	v_exp_f32_e32 v93, v93
	v_cndmask_b32_e32 v88, 0, v88, vcc
	v_cmp_le_i32_e32 vcc, v16, v218
	v_or_b32_e32 v16, 16, v237
	v_add_f32_e32 v221, v84, v221
	v_cndmask_b32_e32 v89, 0, v89, vcc
	v_cmp_le_i32_e32 vcc, v16, v218
	v_or_b32_e32 v16, 17, v237
	v_exp_f32_e32 v94, v94
	v_cndmask_b32_e32 v90, 0, v90, vcc
	v_cmp_le_i32_e32 vcc, v16, v218
	v_or_b32_e32 v16, 18, v237
	v_add_f32_e32 v221, v85, v221
	v_cndmask_b32_e32 v91, 0, v91, vcc
	v_cmp_le_i32_e32 vcc, v16, v218
	v_or_b32_e32 v16, 19, v237
	v_exp_f32_e32 v95, v95
	v_add_f32_e32 v221, v86, v221
	v_cndmask_b32_e32 v92, 0, v92, vcc
	v_cmp_le_i32_e32 vcc, v16, v218
	v_or_b32_e32 v16, 24, v237
	v_cvt_pk_bf16_f32 v82, v82, v83
	v_cvt_pk_bf16_f32 v83, v84, v85
	v_cvt_pk_bf16_f32 v84, v86, v87
	v_cvt_pk_bf16_f32 v85, v88, v89
	v_add_f32_e32 v221, v87, v221
	v_cndmask_b32_e32 v93, 0, v93, vcc
	v_cmp_le_i32_e32 vcc, v16, v218
	v_or_b32_e32 v16, 25, v237
	v_mfma_f32_32x32x16_bf16 v[66:81], v[134:137], v[82:85], 0
	v_add_f32_e32 v221, v88, v221
	v_cndmask_b32_e32 v94, 0, v94, vcc
	v_exp_f32_e32 v86, v96
	v_cmp_le_i32_e32 vcc, v16, v218
	v_or_b32_e32 v88, 26, v237
	v_add_f32_e32 v221, v89, v221
	v_cndmask_b32_e32 v87, 0, v95, vcc
	v_mfma_f32_32x32x16_bf16 v[50:65], v[130:133], v[82:85], 0
	v_cmp_le_i32_e32 vcc, v88, v218
	v_exp_f32_e32 v88, v97
	v_or_b32_e32 v82, 27, v237
	v_cndmask_b32_e32 v86, 0, v86, vcc
	v_cmp_le_i32_e32 vcc, v82, v218
	v_cvt_pk_bf16_f32 v82, v90, v91
	v_cvt_pk_bf16_f32 v83, v92, v93
	v_cndmask_b32_e32 v88, 0, v88, vcc
	v_cvt_pk_bf16_f32 v84, v94, v87
	v_cvt_pk_bf16_f32 v85, v86, v88
	v_add_f32_e32 v221, v90, v221
	v_add_f32_e32 v89, v91, v221
	v_mfma_f32_32x32x16_bf16 v[66:81], v[118:121], v[82:85], v[66:81]
	v_add_f32_e32 v89, v92, v89
	v_add_f32_e32 v89, v93, v89
	v_add_f32_e32 v89, v94, v89
	v_add_f32_e32 v87, v87, v89
	v_add_f32_e32 v86, v86, v87
	v_add_f32_e32 v221, v88, v86
	v_mfma_f32_32x32x16_bf16 v[50:65], v[102:105], v[82:85], v[50:65]
	s_cmp_lg_u32 s85, s86
	s_cbranch_scc1 .Lq_nl0_k1p0
	s_min_u32 s14, s87, 63
	s_nop 3
	v_readlane_b32 s30, v33, s14
	s_and_b32 s30, s30, 0xff
	s_lshl_b32 s30, s30, 13
	s_or_b32 s30, s30, 0x1000
	s_add_u32 s64, s11, s30
	s_addc_u32 s65, s12, 0
	s_add_u32 s66, s8, s30
	s_addc_u32 s67, s9, 0
	global_load_dwordx4 v[194:197], v2, s[64:65]
	global_load_dwordx4 v[190:193], v2, s[64:65] offset:1024
	global_load_dwordx4 v[186:189], v2, s[64:65] offset:2048
	global_load_dwordx4 v[182:185], v2, s[64:65] offset:3072
	global_load_dwordx4 v[134:137], v2, s[66:67]
	global_load_dwordx4 v[130:133], v2, s[66:67] offset:1024
	global_load_dwordx4 v[118:121], v2, s[66:67] offset:2048
	global_load_dwordx4 v[102:105], v2, s[66:67] offset:3072
	s_waitcnt vmcnt(20)
	s_branch .Lq_nl0d_k1p0

.Lq_wd_k1p1:
	v_bfe_u32 v28, s57, v18, 6
	v_lshl_add_u32 v218, s99, 6, v28
	v_mad_u32_u24 v21, v28, s82, v19
	v_mad_u32_u24 v32, v28, s82, v31
	v_and_b32_e32 v29, s18, v23
	v_cmp_ne_u32_e64 s[54:55], 0, v29
	s_and_b64 s[54:55], s[54:55], s[94:95]
	s_min_u32 s14, s85, 63
	s_nop 3
	v_readlane_b32 s30, v26, s14
	v_readlane_b32 s31, v27, s14
	v_bfe_u32 v28, s31, v18, 6
	v_lshl_add_u32 v29, s99, 6, v28
	v_mad_u32_u24 v29, v29, s47, v20
	global_load_dwordx4 v[4:7], v29, s[20:21]
	global_load_dwordx4 v[8:11], v29, s[20:21] offset:32
	global_load_dwordx4 v[12:15], v29, s[20:21] offset:64
	global_load_dwordx4 v[98:101], v29, s[20:21] offset:96
	s_lshl_b32 s0, s100, 6
	v_or_b32_e32 v237, s0, v206
	v_mov_b32_e32 v221, 0
	s_cmp_lg_u32 s100, s99
	s_cbranch_scc1 .Lq_s0n_k1p1
	v_and_b32_e32 v82, s18, v23
	v_cmp_ne_u32_e32 vcc, 0, v82
	s_and_b64 vcc, s[94:95], vcc
	v_mov_b32 v83, 0
	v_or_b32_e32 v16, 2, v237
	v_cndmask_b32_e32 v82, v236, v222, vcc
	v_sub_f32_e32 v82, v83, v82
	v_mov_b32_e32 v83, v82
	v_mov_b32_e32 v84, v82
	v_mov_b32_e32 v85, v82
	v_mov_b32_e32 v86, v82
	v_mov_b32_e32 v87, v82
	v_mov_b32_e32 v88, v82
	v_mov_b32_e32 v89, v82
	v_mov_b32_e32 v90, v82
	v_mov_b32_e32 v91, v82
	v_mov_b32_e32 v92, v82
	v_mov_b32_e32 v93, v82
	v_mov_b32_e32 v94, v82
	v_mov_b32_e32 v95, v82
	v_mov_b32_e32 v96, v82
	v_mov_b32_e32 v97, v82
	v_cmp_le_i32_e32 vcc, v237, v218
	v_or_b32_e32 v17, 3, v237
	v_mfma_f32_32x32x16_bf16 v[82:97], v[194:197], v[238:241], v[82:97]
	v_or_b32_e32 v30, 8, v237
	v_mfma_f32_32x32x16_bf16 v[82:97], v[190:193], v[242:245], v[82:97]
	v_mfma_f32_32x32x16_bf16 v[82:97], v[186:189], v[246:249], v[82:97]
	v_mfma_f32_32x32x16_bf16 v[82:97], v[182:185], v[250:253], v[82:97]
	s_nop 11
	v_exp_f32_e32 v82, v82
	v_exp_f32_e32 v83, v83
	v_exp_f32_e32 v84, v84
	v_exp_f32_e32 v85, v85
	v_exp_f32_e32 v86, v86
	v_cndmask_b32_e32 v82, 0, v82, vcc
	v_cmp_lt_i32_e32 vcc, v237, v218
	v_exp_f32_e32 v87, v87
	v_exp_f32_e32 v88, v88
	v_cndmask_b32_e32 v83, 0, v83, vcc
	v_cmp_le_i32_e32 vcc, v16, v218
	v_or_b32_e32 v16, 9, v237
	v_exp_f32_e32 v89, v89
	v_cndmask_b32_e32 v84, 0, v84, vcc
	v_cmp_le_i32_e32 vcc, v17, v218
	v_exp_f32_e32 v90, v90
	v_exp_f32_e32 v91, v91
	v_cndmask_b32_e32 v85, 0, v85, vcc
	v_cmp_le_i32_e32 vcc, v30, v218
	v_add_f32_e32 v221, v221, v82
	v_exp_f32_e32 v92, v92
	v_cndmask_b32_e32 v86, 0, v86, vcc
	v_cmp_le_i32_e32 vcc, v16, v218
	v_or_b32_e32 v16, 10, v237
	v_add_f32_e32 v221, v83, v221
	v_cndmask_b32_e32 v87, 0, v87, vcc
	v_cmp_le_i32_e32 vcc, v16, v218
	v_or_b32_e32 v16, 11, v237
	v_exp_f32_e32 v93, v93
	v_cndmask_b32_e32 v88, 0, v88, vcc
	v_cmp_le_i32_e32 vcc, v16, v218
	v_or_b32_e32 v16, 16, v237
	v_add_f32_e32 v221, v84, v221
	v_cndmask_b32_e32 v89, 0, v89, vcc
	v_cmp_le_i32_e32 vcc, v16, v218
	v_or_b32_e32 v16, 17, v237
	v_exp_f32_e32 v94, v94
	v_cndmask_b32_e32 v90, 0, v90, vcc
	v_cmp_le_i32_e32 vcc, v16, v218
	v_or_b32_e32 v16, 18, v237
	v_add_f32_e32 v221, v85, v221
	v_cndmask_b32_e32 v91, 0, v91, vcc
	v_cmp_le_i32_e32 vcc, v16, v218
	v_or_b32_e32 v16, 19, v237
	v_exp_f32_e32 v95, v95
	v_add_f32_e32 v221, v86, v221
	v_cndmask_b32_e32 v92, 0, v92, vcc
	v_cmp_le_i32_e32 vcc, v16, v218
	v_or_b32_e32 v16, 24, v237
	v_cvt_pk_bf16_f32 v82, v82, v83
	v_cvt_pk_bf16_f32 v83, v84, v85
	v_cvt_pk_bf16_f32 v84, v86, v87
	v_cvt_pk_bf16_f32 v85, v88, v89
	v_add_f32_e32 v221, v87, v221
	v_cndmask_b32_e32 v93, 0, v93, vcc
	v_cmp_le_i32_e32 vcc, v16, v218
	v_or_b32_e32 v16, 25, v237
	v_mfma_f32_32x32x16_bf16 v[66:81], v[134:137], v[82:85], 0
	v_add_f32_e32 v221, v88, v221
	v_cndmask_b32_e32 v94, 0, v94, vcc
	v_exp_f32_e32 v86, v96
	v_cmp_le_i32_e32 vcc, v16, v218
	v_or_b32_e32 v88, 26, v237
	v_add_f32_e32 v221, v89, v221
	v_cndmask_b32_e32 v87, 0, v95, vcc
	v_mfma_f32_32x32x16_bf16 v[50:65], v[130:133], v[82:85], 0
	v_cmp_le_i32_e32 vcc, v88, v218
	v_exp_f32_e32 v88, v97
	v_or_b32_e32 v82, 27, v237
	v_cndmask_b32_e32 v86, 0, v86, vcc
	v_cmp_le_i32_e32 vcc, v82, v218
	v_cvt_pk_bf16_f32 v82, v90, v91
	v_cvt_pk_bf16_f32 v83, v92, v93
	v_cndmask_b32_e32 v88, 0, v88, vcc
	v_cvt_pk_bf16_f32 v84, v94, v87
	v_cvt_pk_bf16_f32 v85, v86, v88
	v_add_f32_e32 v221, v90, v221
	v_add_f32_e32 v89, v91, v221
	v_mfma_f32_32x32x16_bf16 v[66:81], v[118:121], v[82:85], v[66:81]
	v_add_f32_e32 v89, v92, v89
	v_add_f32_e32 v89, v93, v89
	v_add_f32_e32 v89, v94, v89
	v_add_f32_e32 v87, v87, v89
	v_add_f32_e32 v86, v86, v87
	v_add_f32_e32 v221, v88, v86
	v_mfma_f32_32x32x16_bf16 v[50:65], v[102:105], v[82:85], v[50:65]
	s_cmp_lg_u32 s85, s86
	s_cbranch_scc1 .Lq_nl0_k1p1
	s_min_u32 s14, s87, 63
	s_nop 3
	v_readlane_b32 s30, v33, s14
	s_and_b32 s30, s30, 0xff
	s_lshl_b32 s30, s30, 13
	s_or_b32 s30, s30, 0x1000
	s_add_u32 s64, s11, s30
	s_addc_u32 s65, s12, 0
	s_add_u32 s66, s8, s30
	s_addc_u32 s67, s9, 0
	global_load_dwordx4 v[194:197], v2, s[64:65]
	global_load_dwordx4 v[190:193], v2, s[64:65] offset:1024
	global_load_dwordx4 v[186:189], v2, s[64:65] offset:2048
	global_load_dwordx4 v[182:185], v2, s[64:65] offset:3072
	global_load_dwordx4 v[134:137], v2, s[66:67]
	global_load_dwordx4 v[130:133], v2, s[66:67] offset:1024
	global_load_dwordx4 v[118:121], v2, s[66:67] offset:2048
	global_load_dwordx4 v[102:105], v2, s[66:67] offset:3072
	s_waitcnt vmcnt(20)
	s_branch .Lq_nl0d_k1p1

.Lq_nl0d_k1p1:
	s_lshl_b32 s0, s100, 6
	s_or_b32 s0, s0, 32
	v_or_b32_e32 v237, s0, v206
	v_and_b32_e32 v82, s18, v23
	v_cmp_ne_u32_e32 vcc, 0, v82
	s_and_b64 vcc, s[94:95], vcc
	v_mov_b32 v83, 0
	v_or_b32_e32 v16, 2, v237
	v_cndmask_b32_e32 v82, v236, v222, vcc
	v_sub_f32_e32 v82, v83, v82
	v_mov_b32_e32 v83, v82
	v_mov_b32_e32 v84, v82
	v_mov_b32_e32 v85, v82
	v_mov_b32_e32 v86, v82
	v_mov_b32_e32 v87, v82
	v_mov_b32_e32 v88, v82
	v_mov_b32_e32 v89, v82
	v_mov_b32_e32 v90, v82
	v_mov_b32_e32 v91, v82
	v_mov_b32_e32 v92, v82
	v_mov_b32_e32 v93, v82
	v_mov_b32_e32 v94, v82
	v_mov_b32_e32 v95, v82
	v_mov_b32_e32 v96, v82
	v_mov_b32_e32 v97, v82
	v_cmp_le_i32_e32 vcc, v237, v218
	v_or_b32_e32 v17, 3, v237
	v_mfma_f32_32x32x16_bf16 v[82:97], v[178:181], v[238:241], v[82:97]
	v_or_b32_e32 v30, 8, v237
	v_mfma_f32_32x32x16_bf16 v[82:97], v[174:177], v[242:245], v[82:97]
	v_mfma_f32_32x32x16_bf16 v[82:97], v[170:173], v[246:249], v[82:97]
	v_mfma_f32_32x32x16_bf16 v[82:97], v[166:169], v[250:253], v[82:97]
	s_nop 11
	v_exp_f32_e32 v82, v82
	v_exp_f32_e32 v83, v83
	v_exp_f32_e32 v84, v84
	v_exp_f32_e32 v85, v85
	v_exp_f32_e32 v86, v86
	v_cndmask_b32_e32 v82, 0, v82, vcc
	v_cmp_lt_i32_e32 vcc, v237, v218
	v_exp_f32_e32 v87, v87
	v_exp_f32_e32 v88, v88
	v_cndmask_b32_e32 v83, 0, v83, vcc
	v_cmp_le_i32_e32 vcc, v16, v218
	v_or_b32_e32 v16, 9, v237
	v_exp_f32_e32 v89, v89
	v_cndmask_b32_e32 v84, 0, v84, vcc
	v_cmp_le_i32_e32 vcc, v17, v218
	v_exp_f32_e32 v90, v90
	v_exp_f32_e32 v91, v91
	v_cndmask_b32_e32 v85, 0, v85, vcc
	v_cmp_le_i32_e32 vcc, v30, v218
	v_add_f32_e32 v221, v221, v82
	v_exp_f32_e32 v92, v92
	v_cndmask_b32_e32 v86, 0, v86, vcc
	v_cmp_le_i32_e32 vcc, v16, v218
	v_or_b32_e32 v16, 10, v237
	v_add_f32_e32 v221, v83, v221
	v_cndmask_b32_e32 v87, 0, v87, vcc
	v_cmp_le_i32_e32 vcc, v16, v218
	v_or_b32_e32 v16, 11, v237
	v_exp_f32_e32 v93, v93
	v_cndmask_b32_e32 v88, 0, v88, vcc
	v_cmp_le_i32_e32 vcc, v16, v218
	v_or_b32_e32 v16, 16, v237
	v_add_f32_e32 v221, v84, v221
	v_cndmask_b32_e32 v89, 0, v89, vcc
	v_cmp_le_i32_e32 vcc, v16, v218
	v_or_b32_e32 v16, 17, v237
	v_exp_f32_e32 v94, v94
	v_cndmask_b32_e32 v90, 0, v90, vcc
	v_cmp_le_i32_e32 vcc, v16, v218
	v_or_b32_e32 v16, 18, v237
	v_add_f32_e32 v221, v85, v221
	v_cndmask_b32_e32 v91, 0, v91, vcc
	v_cmp_le_i32_e32 vcc, v16, v218
	v_or_b32_e32 v16, 19, v237
	v_exp_f32_e32 v95, v95
	v_add_f32_e32 v221, v86, v221
	v_cndmask_b32_e32 v92, 0, v92, vcc
	v_cmp_le_i32_e32 vcc, v16, v218
	v_or_b32_e32 v16, 24, v237
	v_cvt_pk_bf16_f32 v82, v82, v83
	v_cvt_pk_bf16_f32 v83, v84, v85
	v_cvt_pk_bf16_f32 v84, v86, v87
	v_cvt_pk_bf16_f32 v85, v88, v89
	v_add_f32_e32 v221, v87, v221
	v_cndmask_b32_e32 v93, 0, v93, vcc
	v_cmp_le_i32_e32 vcc, v16, v218
	v_or_b32_e32 v16, 25, v237
	v_mfma_f32_32x32x16_bf16 v[66:81], v[146:149], v[82:85], v[66:81]
	v_add_f32_e32 v221, v88, v221
	v_cndmask_b32_e32 v94, 0, v94, vcc
	v_exp_f32_e32 v86, v96
	v_cmp_le_i32_e32 vcc, v16, v218
	v_or_b32_e32 v88, 26, v237
	v_add_f32_e32 v221, v89, v221
	v_cndmask_b32_e32 v87, 0, v95, vcc
	v_mfma_f32_32x32x16_bf16 v[50:65], v[142:145], v[82:85], v[50:65]
	v_cmp_le_i32_e32 vcc, v88, v218
	v_exp_f32_e32 v88, v97
	v_or_b32_e32 v82, 27, v237
	v_cndmask_b32_e32 v86, 0, v86, vcc
	v_cmp_le_i32_e32 vcc, v82, v218
	v_cvt_pk_bf16_f32 v82, v90, v91
	v_cvt_pk_bf16_f32 v83, v92, v93
	v_cndmask_b32_e32 v88, 0, v88, vcc
	v_cvt_pk_bf16_f32 v84, v94, v87
	v_cvt_pk_bf16_f32 v85, v86, v88
	v_add_f32_e32 v221, v90, v221
	v_add_f32_e32 v89, v91, v221
	v_mfma_f32_32x32x16_bf16 v[66:81], v[126:129], v[82:85], v[66:81]
	v_add_f32_e32 v89, v92, v89
	v_add_f32_e32 v89, v93, v89
	v_add_f32_e32 v89, v94, v89
	v_add_f32_e32 v87, v87, v89
	v_add_f32_e32 v86, v86, v87
	v_add_f32_e32 v221, v88, v86
	v_mfma_f32_32x32x16_bf16 v[50:65], v[114:117], v[82:85], v[50:65]
	s_cmp_lg_u32 s85, s86
	s_cbranch_scc1 .Lq_nl1_k1p1
	s_min_u32 s14, s88, 63
	s_nop 3
	v_readlane_b32 s30, v33, s14
	s_and_b32 s30, s30, 0xff
	s_lshl_b32 s30, s30, 13
	s_add_u32 s64, s11, s30
	s_addc_u32 s65, s12, 0
	s_add_u32 s66, s8, s30
	s_addc_u32 s67, s9, 0
	global_load_dwordx4 v[178:181], v2, s[64:65]
	global_load_dwordx4 v[174:177], v2, s[64:65] offset:1024
	global_load_dwordx4 v[170:173], v2, s[64:65] offset:2048
	global_load_dwordx4 v[166:169], v2, s[64:65] offset:3072
	global_load_dwordx4 v[146:149], v2, s[66:67]
	global_load_dwordx4 v[142:145], v2, s[66:67] offset:1024
	global_load_dwordx4 v[126:129], v2, s[66:67] offset:2048
	global_load_dwordx4 v[114:117], v2, s[66:67] offset:3072
	s_branch .Lq_nl1_k1p1
.Lq_s0n_k1p1:
	v_and_b32_e32 v82, s18, v23
	v_cmp_ne_u32_e32 vcc, 0, v82
	s_and_b64 vcc, s[94:95], vcc
	v_mov_b32 v83, 0
	v_cndmask_b32_e32 v82, v236, v222, vcc
	v_sub_f32_e32 v82, v83, v82
	v_mov_b32_e32 v83, v82
	v_mov_b32_e32 v84, v82
	v_mov_b32_e32 v85, v82
	v_mov_b32_e32 v86, v82
	v_mov_b32_e32 v87, v82
	v_mov_b32_e32 v88, v82
	v_mov_b32_e32 v89, v82
	v_mov_b32_e32 v90, v82
	v_mov_b32_e32 v91, v82
	v_mov_b32_e32 v92, v82
	v_mov_b32_e32 v93, v82
	v_mov_b32_e32 v94, v82
	v_mov_b32_e32 v95, v82
	v_mov_b32_e32 v96, v82
	v_mov_b32_e32 v97, v82
	s_nop 1
	v_mfma_f32_32x32x16_bf16 v[82:97], v[194:197], v[238:241], v[82:97]
	v_mfma_f32_32x32x16_bf16 v[82:97], v[190:193], v[242:245], v[82:97]
	v_mfma_f32_32x32x16_bf16 v[82:97], v[186:189], v[246:249], v[82:97]
	v_mfma_f32_32x32x16_bf16 v[82:97], v[182:185], v[250:253], v[82:97]
	s_waitcnt vmcnt(12)
	v_mov_b32_e32 v28, 0
	v_and_b32_e32 v34, s18, v23
	v_cmp_ne_u32_e32 vcc, 0, v34
	s_and_b64 vcc, s[94:95], vcc
	v_mov_b32 v35, 0
	v_cndmask_b32_e32 v34, v236, v222, vcc
	v_sub_f32_e32 v34, v35, v34
	v_mov_b32_e32 v35, v34
	v_mov_b32_e32 v36, v34
	v_mov_b32_e32 v37, v34
	v_mov_b32_e32 v38, v34
	v_mov_b32_e32 v39, v34
	v_mov_b32_e32 v40, v34
	v_mov_b32_e32 v41, v34
	v_mov_b32_e32 v42, v34
	v_mov_b32_e32 v43, v34
	v_mov_b32_e32 v44, v34
	v_mov_b32_e32 v45, v34
	v_mov_b32_e32 v46, v34
	v_mov_b32_e32 v47, v34
	v_mov_b32_e32 v48, v34
	v_mov_b32_e32 v49, v34
	s_nop 1
	v_mfma_f32_32x32x16_bf16 v[34:49], v[178:181], v[238:241], v[34:49]
	v_mfma_f32_32x32x16_bf16 v[34:49], v[174:177], v[242:245], v[34:49]
	v_mfma_f32_32x32x16_bf16 v[34:49], v[170:173], v[246:249], v[34:49]
	v_mfma_f32_32x32x16_bf16 v[34:49], v[166:169], v[250:253], v[34:49]
	v_exp_f32_e32 v82, v82
	v_exp_f32_e32 v83, v83
	v_exp_f32_e32 v84, v84
	v_exp_f32_e32 v85, v85
	v_exp_f32_e32 v86, v86
	v_exp_f32_e32 v87, v87
	v_exp_f32_e32 v88, v88
	v_exp_f32_e32 v89, v89
	v_exp_f32_e32 v90, v90
	v_exp_f32_e32 v91, v91
	v_add_f32_e32 v221, v221, v82
	v_exp_f32_e32 v92, v92
	v_exp_f32_e32 v34, v34
	v_add_f32_e32 v221, v83, v221
	v_exp_f32_e32 v35, v35
	v_exp_f32_e32 v93, v93
	v_exp_f32_e32 v36, v36
	v_add_f32_e32 v221, v84, v221
	v_exp_f32_e32 v37, v37
	v_exp_f32_e32 v94, v94
	v_exp_f32_e32 v38, v38
	v_add_f32_e32 v221, v85, v221
	v_exp_f32_e32 v39, v39
	v_exp_f32_e32 v95, v95
	v_exp_f32_e32 v40, v40
	v_add_f32_e32 v221, v86, v221
	v_exp_f32_e32 v41, v41
	v_cvt_pk_bf16_f32 v82, v82, v83
	v_exp_f32_e32 v42, v42
	v_cvt_pk_bf16_f32 v83, v84, v85
	v_exp_f32_e32 v43, v43
	v_cvt_pk_bf16_f32 v84, v86, v87
	v_add_f32_e32 v28, v28, v34
	v_cvt_pk_bf16_f32 v85, v88, v89
	v_exp_f32_e32 v44, v44
	v_add_f32_e32 v221, v87, v221
	v_add_f32_e32 v28, v35, v28
	v_mfma_f32_32x32x16_bf16 v[66:81], v[134:137], v[82:85], 0
	v_exp_f32_e32 v45, v45
	v_add_f32_e32 v221, v88, v221
	v_add_f32_e32 v28, v36, v28
	v_exp_f32_e32 v86, v96
	v_exp_f32_e32 v46, v46
	v_add_f32_e32 v221, v89, v221
	v_add_f32_e32 v28, v37, v28
	v_mov_b32_e32 v87, v95
	v_exp_f32_e32 v47, v47
	v_mfma_f32_32x32x16_bf16 v[50:65], v[130:133], v[82:85], 0
	v_add_f32_e32 v28, v38, v28
	v_exp_f32_e32 v88, v97
	v_cvt_pk_bf16_f32 v34, v34, v35
	v_cvt_pk_bf16_f32 v82, v90, v91
	v_cvt_pk_bf16_f32 v35, v36, v37
	v_cvt_pk_bf16_f32 v83, v92, v93
	v_cvt_pk_bf16_f32 v36, v38, v39
	v_cvt_pk_bf16_f32 v84, v94, v87
	v_cvt_pk_bf16_f32 v37, v40, v41
	v_cvt_pk_bf16_f32 v85, v86, v88
	v_add_f32_e32 v28, v39, v28
	v_add_f32_e32 v221, v90, v221
	v_mfma_f32_32x32x16_bf16 v[66:81], v[146:149], v[34:37], v[66:81]
	v_add_f32_e32 v89, v91, v221
	v_add_f32_e32 v28, v40, v28
	v_mfma_f32_32x32x16_bf16 v[66:81], v[118:121], v[82:85], v[66:81]
	v_exp_f32_e32 v38, v48
	v_add_f32_e32 v89, v92, v89
	v_add_f32_e32 v28, v41, v28
	v_add_f32_e32 v89, v93, v89
	v_mov_b32_e32 v39, v47
	v_add_f32_e32 v89, v94, v89
	v_mfma_f32_32x32x16_bf16 v[50:65], v[142:145], v[34:37], v[50:65]
	v_add_f32_e32 v87, v87, v89
	v_exp_f32_e32 v40, v49
	v_add_f32_e32 v86, v86, v87
	v_cvt_pk_bf16_f32 v34, v42, v43
	v_add_f32_e32 v221, v88, v86
	v_cvt_pk_bf16_f32 v35, v44, v45
	v_mfma_f32_32x32x16_bf16 v[50:65], v[102:105], v[82:85], v[50:65]
	v_cvt_pk_bf16_f32 v36, v46, v39
	v_cvt_pk_bf16_f32 v37, v38, v40
	v_add_f32_e32 v28, v42, v28
	v_add_f32_e32 v41, v43, v28
	v_mfma_f32_32x32x16_bf16 v[66:81], v[126:129], v[34:37], v[66:81]
	v_add_f32_e32 v41, v44, v41
	v_add_f32_e32 v41, v45, v41
	v_add_f32_e32 v41, v46, v41
	v_add_f32_e32 v39, v39, v41
	v_add_f32_e32 v38, v38, v39
	v_add_f32_e32 v28, v40, v38
	v_mfma_f32_32x32x16_bf16 v[50:65], v[114:117], v[34:37], v[50:65]
	v_add_f32_e32 v221, v221, v28
	s_cmp_lg_u32 s85, s86
	s_cbranch_scc1 .Lq_nl1_k1p1
	s_min_u32 s14, s87, 63
	s_nop 3
	v_readlane_b32 s30, v33, s14
	s_and_b32 s30, s30, 0xff
	s_lshl_b32 s30, s30, 13
	s_or_b32 s30, s30, 0x1000
	s_add_u32 s64, s11, s30
	s_addc_u32 s65, s12, 0
	s_add_u32 s66, s8, s30
	s_addc_u32 s67, s9, 0
	global_load_dwordx4 v[194:197], v2, s[64:65]
	global_load_dwordx4 v[190:193], v2, s[64:65] offset:1024
	global_load_dwordx4 v[186:189], v2, s[64:65] offset:2048
	global_load_dwordx4 v[182:185], v2, s[64:65] offset:3072
	global_load_dwordx4 v[134:137], v2, s[66:67]
	global_load_dwordx4 v[130:133], v2, s[66:67] offset:1024
	global_load_dwordx4 v[118:121], v2, s[66:67] offset:2048
	global_load_dwordx4 v[102:105], v2, s[66:67] offset:3072
	s_min_u32 s14, s88, 63
	s_nop 3
	v_readlane_b32 s30, v33, s14
	s_and_b32 s30, s30, 0xff
	s_lshl_b32 s30, s30, 13
	s_add_u32 s64, s11, s30
	s_addc_u32 s65, s12, 0
	s_add_u32 s66, s8, s30
	s_addc_u32 s67, s9, 0
	global_load_dwordx4 v[178:181], v2, s[64:65]
	global_load_dwordx4 v[174:177], v2, s[64:65] offset:1024
	global_load_dwordx4 v[170:173], v2, s[64:65] offset:2048
	global_load_dwordx4 v[166:169], v2, s[64:65] offset:3072
	global_load_dwordx4 v[146:149], v2, s[66:67]
	global_load_dwordx4 v[142:145], v2, s[66:67] offset:1024
	global_load_dwordx4 v[126:129], v2, s[66:67] offset:2048
	global_load_dwordx4 v[114:117], v2, s[66:67] offset:3072

.Lq_vend_k1:
.Lq_visit_k2:
	s_lshr_b32 s84, s52, 1
	s_add_i32 s84, s84, 2
	s_cmp_ge_u32 s84, s89
	s_cbranch_scc1 .Lq_loop_end
	s_min_u32 s14, s84, 63
	s_nop 3
	v_readlane_b32 s0, v33, s14
	s_and_b32 s100, s0, 0xff
	s_lshr_b32 s68, s0, 8
	s_mov_b32 s91, s68
	s_add_i32 s1, s84, 1
	s_min_u32 s14, s1, 63
	s_nop 3
	v_readlane_b32 s86, v33, s14
	s_lshr_b32 s86, s86, 8
	s_cmp_ge_u32 s1, s89
	s_cselect_b32 s86, s10, s86
	s_add_i32 s87, s84, 1
	s_add_i32 s88, s84, 2

.Lq_wd_k2p0:
	v_bfe_u32 v28, s57, v18, 6
	v_lshl_add_u32 v218, s99, 6, v28
	v_mad_u32_u24 v21, v28, s82, v19
	v_mad_u32_u24 v32, v28, s82, v31
	v_and_b32_e32 v29, s18, v23
	v_cmp_ne_u32_e64 s[54:55], 0, v29
	s_and_b64 s[54:55], s[54:55], s[94:95]
	s_min_u32 s14, s85, 63
	s_nop 3
	v_readlane_b32 s30, v26, s14
	v_readlane_b32 s31, v27, s14
	v_bfe_u32 v28, s31, v18, 6
	v_lshl_add_u32 v29, s99, 6, v28
	v_mad_u32_u24 v29, v29, s47, v20
	global_load_dwordx4 v[238:241], v29, s[20:21]
	global_load_dwordx4 v[242:245], v29, s[20:21] offset:32
	global_load_dwordx4 v[246:249], v29, s[20:21] offset:64
	global_load_dwordx4 v[250:253], v29, s[20:21] offset:96
	s_lshl_b32 s0, s100, 6
	v_or_b32_e32 v237, s0, v206
	v_mov_b32_e32 v221, 0
	s_cmp_lg_u32 s100, s99
	s_cbranch_scc1 .Lq_s0n_k2p0
	v_and_b32_e32 v82, s18, v23
	v_cmp_ne_u32_e32 vcc, 0, v82
	s_and_b64 vcc, s[94:95], vcc
	v_mov_b32 v83, 0
	v_or_b32_e32 v16, 2, v237
	v_cndmask_b32_e32 v82, v236, v222, vcc
	v_sub_f32_e32 v82, v83, v82
	v_mov_b32_e32 v83, v82
	v_mov_b32_e32 v84, v82
	v_mov_b32_e32 v85, v82
	v_mov_b32_e32 v86, v82
	v_mov_b32_e32 v87, v82
	v_mov_b32_e32 v88, v82
	v_mov_b32_e32 v89, v82
	v_mov_b32_e32 v90, v82
	v_mov_b32_e32 v91, v82
	v_mov_b32_e32 v92, v82
	v_mov_b32_e32 v93, v82
	v_mov_b32_e32 v94, v82
	v_mov_b32_e32 v95, v82
	v_mov_b32_e32 v96, v82
	v_mov_b32_e32 v97, v82
	v_cmp_le_i32_e32 vcc, v237, v218
	v_or_b32_e32 v17, 3, v237
	v_mfma_f32_32x32x16_bf16 v[82:97], v[162:165], v[4:7], v[82:97]
	v_or_b32_e32 v30, 8, v237
	v_mfma_f32_32x32x16_bf16 v[82:97], v[154:157], v[8:11], v[82:97]
	v_mfma_f32_32x32x16_bf16 v[82:97], v[150:153], v[12:15], v[82:97]
	v_mfma_f32_32x32x16_bf16 v[82:97], v[158:161], v[98:101], v[82:97]
	s_nop 11
	v_exp_f32_e32 v82, v82
	v_exp_f32_e32 v83, v83
	v_exp_f32_e32 v84, v84
	v_exp_f32_e32 v85, v85
	v_exp_f32_e32 v86, v86
	v_cndmask_b32_e32 v82, 0, v82, vcc
	v_cmp_lt_i32_e32 vcc, v237, v218
	v_exp_f32_e32 v87, v87
	v_exp_f32_e32 v88, v88
	v_cndmask_b32_e32 v83, 0, v83, vcc
	v_cmp_le_i32_e32 vcc, v16, v218
	v_or_b32_e32 v16, 9, v237
	v_exp_f32_e32 v89, v89
	v_cndmask_b32_e32 v84, 0, v84, vcc
	v_cmp_le_i32_e32 vcc, v17, v218
	v_exp_f32_e32 v90, v90
	v_exp_f32_e32 v91, v91
	v_cndmask_b32_e32 v85, 0, v85, vcc
	v_cmp_le_i32_e32 vcc, v30, v218
	v_add_f32_e32 v221, v221, v82
	v_exp_f32_e32 v92, v92
	v_cndmask_b32_e32 v86, 0, v86, vcc
	v_cmp_le_i32_e32 vcc, v16, v218
	v_or_b32_e32 v16, 10, v237
	v_add_f32_e32 v221, v83, v221
	v_cndmask_b32_e32 v87, 0, v87, vcc
	v_cmp_le_i32_e32 vcc, v16, v218
	v_or_b32_e32 v16, 11, v237
	v_exp_f32_e32 v93, v93
	v_cndmask_b32_e32 v88, 0, v88, vcc
	v_cmp_le_i32_e32 vcc, v16, v218
	v_or_b32_e32 v16, 16, v237
	v_add_f32_e32 v221, v84, v221
	v_cndmask_b32_e32 v89, 0, v89, vcc
	v_cmp_le_i32_e32 vcc, v16, v218
	v_or_b32_e32 v16, 17, v237
	v_exp_f32_e32 v94, v94
	v_cndmask_b32_e32 v90, 0, v90, vcc
	v_cmp_le_i32_e32 vcc, v16, v218
	v_or_b32_e32 v16, 18, v237
	v_add_f32_e32 v221, v85, v221
	v_cndmask_b32_e32 v91, 0, v91, vcc
	v_cmp_le_i32_e32 vcc, v16, v218
	v_or_b32_e32 v16, 19, v237
	v_exp_f32_e32 v95, v95
	v_add_f32_e32 v221, v86, v221
	v_cndmask_b32_e32 v92, 0, v92, vcc
	v_cmp_le_i32_e32 vcc, v16, v218
	v_or_b32_e32 v16, 24, v237
	v_cvt_pk_bf16_f32 v82, v82, v83
	v_cvt_pk_bf16_f32 v83, v84, v85
	v_cvt_pk_bf16_f32 v84, v86, v87
	v_cvt_pk_bf16_f32 v85, v88, v89
	v_add_f32_e32 v221, v87, v221
	v_cndmask_b32_e32 v93, 0, v93, vcc
	v_cmp_le_i32_e32 vcc, v16, v218
	v_or_b32_e32 v16, 25, v237
	v_mfma_f32_32x32x16_bf16 v[66:81], v[138:141], v[82:85], 0
	v_add_f32_e32 v221, v88, v221
	v_cndmask_b32_e32 v94, 0, v94, vcc
	v_exp_f32_e32 v86, v96
	v_cmp_le_i32_e32 vcc, v16, v218
	v_or_b32_e32 v88, 26, v237
	v_add_f32_e32 v221, v89, v221
	v_cndmask_b32_e32 v87, 0, v95, vcc
	v_mfma_f32_32x32x16_bf16 v[50:65], v[122:125], v[82:85], 0
	v_cmp_le_i32_e32 vcc, v88, v218
	v_exp_f32_e32 v88, v97
	v_or_b32_e32 v82, 27, v237
	v_cndmask_b32_e32 v86, 0, v86, vcc
	v_cmp_le_i32_e32 vcc, v82, v218
	v_cvt_pk_bf16_f32 v82, v90, v91
	v_cvt_pk_bf16_f32 v83, v92, v93
	v_cndmask_b32_e32 v88, 0, v88, vcc
	v_cvt_pk_bf16_f32 v84, v94, v87
	v_cvt_pk_bf16_f32 v85, v86, v88
	v_add_f32_e32 v221, v90, v221
	v_add_f32_e32 v89, v91, v221
	v_mfma_f32_32x32x16_bf16 v[66:81], v[110:113], v[82:85], v[66:81]
	v_add_f32_e32 v89, v92, v89
	v_add_f32_e32 v89, v93, v89
	v_add_f32_e32 v89, v94, v89
	v_add_f32_e32 v87, v87, v89
	v_add_f32_e32 v86, v86, v87
	v_add_f32_e32 v221, v88, v86
	v_mfma_f32_32x32x16_bf16 v[50:65], v[106:109], v[82:85], v[50:65]
	s_cmp_lg_u32 s85, s86
	s_cbranch_scc1 .Lq_nl0_k2p0
	s_min_u32 s14, s87, 63
	s_nop 3
	v_readlane_b32 s30, v33, s14
	s_and_b32 s30, s30, 0xff
	s_lshl_b32 s30, s30, 13
	s_or_b32 s30, s30, 0x1000
	s_add_u32 s64, s11, s30
	s_addc_u32 s65, s12, 0
	s_add_u32 s66, s8, s30
	s_addc_u32 s67, s9, 0
	global_load_dwordx4 v[162:165], v2, s[64:65]
	global_load_dwordx4 v[154:157], v2, s[64:65] offset:1024
	global_load_dwordx4 v[150:153], v2, s[64:65] offset:2048
	global_load_dwordx4 v[158:161], v2, s[64:65] offset:3072
	global_load_dwordx4 v[138:141], v2, s[66:67]
	global_load_dwordx4 v[122:125], v2, s[66:67] offset:1024
	global_load_dwordx4 v[110:113], v2, s[66:67] offset:2048
	global_load_dwordx4 v[106:109], v2, s[66:67] offset:3072
	s_waitcnt vmcnt(20)
	s_branch .Lq_nl0d_k2p0

.Lq_wd_k2p1:
	v_bfe_u32 v28, s57, v18, 6
	v_lshl_add_u32 v218, s99, 6, v28
	v_mad_u32_u24 v21, v28, s82, v19
	v_mad_u32_u24 v32, v28, s82, v31
	v_and_b32_e32 v29, s18, v23
	v_cmp_ne_u32_e64 s[54:55], 0, v29
	s_and_b64 s[54:55], s[54:55], s[94:95]
	s_min_u32 s14, s85, 63
	s_nop 3
	v_readlane_b32 s30, v26, s14
	v_readlane_b32 s31, v27, s14
	v_bfe_u32 v28, s31, v18, 6
	v_lshl_add_u32 v29, s99, 6, v28
	v_mad_u32_u24 v29, v29, s47, v20
	global_load_dwordx4 v[4:7], v29, s[20:21]
	global_load_dwordx4 v[8:11], v29, s[20:21] offset:32
	global_load_dwordx4 v[12:15], v29, s[20:21] offset:64
	global_load_dwordx4 v[98:101], v29, s[20:21] offset:96
	s_lshl_b32 s0, s100, 6
	v_or_b32_e32 v237, s0, v206
	v_mov_b32_e32 v221, 0
	s_cmp_lg_u32 s100, s99
	s_cbranch_scc1 .Lq_s0n_k2p1
	v_and_b32_e32 v82, s18, v23
	v_cmp_ne_u32_e32 vcc, 0, v82
	s_and_b64 vcc, s[94:95], vcc
	v_mov_b32 v83, 0
	v_or_b32_e32 v16, 2, v237
	v_cndmask_b32_e32 v82, v236, v222, vcc
	v_sub_f32_e32 v82, v83, v82
	v_mov_b32_e32 v83, v82
	v_mov_b32_e32 v84, v82
	v_mov_b32_e32 v85, v82
	v_mov_b32_e32 v86, v82
	v_mov_b32_e32 v87, v82
	v_mov_b32_e32 v88, v82
	v_mov_b32_e32 v89, v82
	v_mov_b32_e32 v90, v82
	v_mov_b32_e32 v91, v82
	v_mov_b32_e32 v92, v82
	v_mov_b32_e32 v93, v82
	v_mov_b32_e32 v94, v82
	v_mov_b32_e32 v95, v82
	v_mov_b32_e32 v96, v82
	v_mov_b32_e32 v97, v82
	v_cmp_le_i32_e32 vcc, v237, v218
	v_or_b32_e32 v17, 3, v237
	v_mfma_f32_32x32x16_bf16 v[82:97], v[162:165], v[238:241], v[82:97]
	v_or_b32_e32 v30, 8, v237
	v_mfma_f32_32x32x16_bf16 v[82:97], v[154:157], v[242:245], v[82:97]
	v_mfma_f32_32x32x16_bf16 v[82:97], v[150:153], v[246:249], v[82:97]
	v_mfma_f32_32x32x16_bf16 v[82:97], v[158:161], v[250:253], v[82:97]
	s_nop 11
	v_exp_f32_e32 v82, v82
	v_exp_f32_e32 v83, v83
	v_exp_f32_e32 v84, v84
	v_exp_f32_e32 v85, v85
	v_exp_f32_e32 v86, v86
	v_cndmask_b32_e32 v82, 0, v82, vcc
	v_cmp_lt_i32_e32 vcc, v237, v218
	v_exp_f32_e32 v87, v87
	v_exp_f32_e32 v88, v88
	v_cndmask_b32_e32 v83, 0, v83, vcc
	v_cmp_le_i32_e32 vcc, v16, v218
	v_or_b32_e32 v16, 9, v237
	v_exp_f32_e32 v89, v89
	v_cndmask_b32_e32 v84, 0, v84, vcc
	v_cmp_le_i32_e32 vcc, v17, v218
	v_exp_f32_e32 v90, v90
	v_exp_f32_e32 v91, v91
	v_cndmask_b32_e32 v85, 0, v85, vcc
	v_cmp_le_i32_e32 vcc, v30, v218
	v_add_f32_e32 v221, v221, v82
	v_exp_f32_e32 v92, v92
	v_cndmask_b32_e32 v86, 0, v86, vcc
	v_cmp_le_i32_e32 vcc, v16, v218
	v_or_b32_e32 v16, 10, v237
	v_add_f32_e32 v221, v83, v221
	v_cndmask_b32_e32 v87, 0, v87, vcc
	v_cmp_le_i32_e32 vcc, v16, v218
	v_or_b32_e32 v16, 11, v237
	v_exp_f32_e32 v93, v93
	v_cndmask_b32_e32 v88, 0, v88, vcc
	v_cmp_le_i32_e32 vcc, v16, v218
	v_or_b32_e32 v16, 16, v237
	v_add_f32_e32 v221, v84, v221
	v_cndmask_b32_e32 v89, 0, v89, vcc
	v_cmp_le_i32_e32 vcc, v16, v218
	v_or_b32_e32 v16, 17, v237
	v_exp_f32_e32 v94, v94
	v_cndmask_b32_e32 v90, 0, v90, vcc
	v_cmp_le_i32_e32 vcc, v16, v218
	v_or_b32_e32 v16, 18, v237
	v_add_f32_e32 v221, v85, v221
	v_cndmask_b32_e32 v91, 0, v91, vcc
	v_cmp_le_i32_e32 vcc, v16, v218
	v_or_b32_e32 v16, 19, v237
	v_exp_f32_e32 v95, v95
	v_add_f32_e32 v221, v86, v221
	v_cndmask_b32_e32 v92, 0, v92, vcc
	v_cmp_le_i32_e32 vcc, v16, v218
	v_or_b32_e32 v16, 24, v237
	v_cvt_pk_bf16_f32 v82, v82, v83
	v_cvt_pk_bf16_f32 v83, v84, v85
	v_cvt_pk_bf16_f32 v84, v86, v87
	v_cvt_pk_bf16_f32 v85, v88, v89
	v_add_f32_e32 v221, v87, v221
	v_cndmask_b32_e32 v93, 0, v93, vcc
	v_cmp_le_i32_e32 vcc, v16, v218
	v_or_b32_e32 v16, 25, v237
	v_mfma_f32_32x32x16_bf16 v[66:81], v[138:141], v[82:85], 0
	v_add_f32_e32 v221, v88, v221
	v_cndmask_b32_e32 v94, 0, v94, vcc
	v_exp_f32_e32 v86, v96
	v_cmp_le_i32_e32 vcc, v16, v218
	v_or_b32_e32 v88, 26, v237
	v_add_f32_e32 v221, v89, v221
	v_cndmask_b32_e32 v87, 0, v95, vcc
	v_mfma_f32_32x32x16_bf16 v[50:65], v[122:125], v[82:85], 0
	v_cmp_le_i32_e32 vcc, v88, v218
	v_exp_f32_e32 v88, v97
	v_or_b32_e32 v82, 27, v237
	v_cndmask_b32_e32 v86, 0, v86, vcc
	v_cmp_le_i32_e32 vcc, v82, v218
	v_cvt_pk_bf16_f32 v82, v90, v91
	v_cvt_pk_bf16_f32 v83, v92, v93
	v_cndmask_b32_e32 v88, 0, v88, vcc
	v_cvt_pk_bf16_f32 v84, v94, v87
	v_cvt_pk_bf16_f32 v85, v86, v88
	v_add_f32_e32 v221, v90, v221
	v_add_f32_e32 v89, v91, v221
	v_mfma_f32_32x32x16_bf16 v[66:81], v[110:113], v[82:85], v[66:81]
	v_add_f32_e32 v89, v92, v89
	v_add_f32_e32 v89, v93, v89
	v_add_f32_e32 v89, v94, v89
	v_add_f32_e32 v87, v87, v89
	v_add_f32_e32 v86, v86, v87
	v_add_f32_e32 v221, v88, v86
	v_mfma_f32_32x32x16_bf16 v[50:65], v[106:109], v[82:85], v[50:65]
	s_cmp_lg_u32 s85, s86
	s_cbranch_scc1 .Lq_nl0_k2p1
	s_min_u32 s14, s87, 63
	s_nop 3
	v_readlane_b32 s30, v33, s14
	s_and_b32 s30, s30, 0xff
	s_lshl_b32 s30, s30, 13
	s_or_b32 s30, s30, 0x1000
	s_add_u32 s64, s11, s30
	s_addc_u32 s65, s12, 0
	s_add_u32 s66, s8, s30
	s_addc_u32 s67, s9, 0
	global_load_dwordx4 v[162:165], v2, s[64:65]
	global_load_dwordx4 v[154:157], v2, s[64:65] offset:1024
	global_load_dwordx4 v[150:153], v2, s[64:65] offset:2048
	global_load_dwordx4 v[158:161], v2, s[64:65] offset:3072
	global_load_dwordx4 v[138:141], v2, s[66:67]
	global_load_dwordx4 v[122:125], v2, s[66:67] offset:1024
	global_load_dwordx4 v[110:113], v2, s[66:67] offset:2048
	global_load_dwordx4 v[106:109], v2, s[66:67] offset:3072
	s_waitcnt vmcnt(20)
	s_branch .Lq_nl0d_k2p1

.Lq_nl0d_k2p1:
	s_lshl_b32 s0, s100, 6
	s_or_b32 s0, s0, 32
	v_or_b32_e32 v237, s0, v206
	v_and_b32_e32 v82, s18, v23
	v_cmp_ne_u32_e32 vcc, 0, v82
	s_and_b64 vcc, s[94:95], vcc
	v_mov_b32 v83, 0
	v_or_b32_e32 v16, 2, v237
	v_cndmask_b32_e32 v82, v236, v222, vcc
	v_sub_f32_e32 v82, v83, v82
	v_mov_b32_e32 v83, v82
	v_mov_b32_e32 v84, v82
	v_mov_b32_e32 v85, v82
	v_mov_b32_e32 v86, v82
	v_mov_b32_e32 v87, v82
	v_mov_b32_e32 v88, v82
	v_mov_b32_e32 v89, v82
	v_mov_b32_e32 v90, v82
	v_mov_b32_e32 v91, v82
	v_mov_b32_e32 v92, v82
	v_mov_b32_e32 v93, v82
	v_mov_b32_e32 v94, v82
	v_mov_b32_e32 v95, v82
	v_mov_b32_e32 v96, v82
	v_mov_b32_e32 v97, v82
	v_cmp_le_i32_e32 vcc, v237, v218
	v_or_b32_e32 v17, 3, v237
	v_mfma_f32_32x32x16_bf16 v[82:97], v[194:197], v[238:241], v[82:97]
	v_or_b32_e32 v30, 8, v237
	v_mfma_f32_32x32x16_bf16 v[82:97], v[190:193], v[242:245], v[82:97]
	v_mfma_f32_32x32x16_bf16 v[82:97], v[186:189], v[246:249], v[82:97]
	v_mfma_f32_32x32x16_bf16 v[82:97], v[182:185], v[250:253], v[82:97]
	s_nop 11
	v_exp_f32_e32 v82, v82
	v_exp_f32_e32 v83, v83
	v_exp_f32_e32 v84, v84
	v_exp_f32_e32 v85, v85
	v_exp_f32_e32 v86, v86
	v_cndmask_b32_e32 v82, 0, v82, vcc
	v_cmp_lt_i32_e32 vcc, v237, v218
	v_exp_f32_e32 v87, v87
	v_exp_f32_e32 v88, v88
	v_cndmask_b32_e32 v83, 0, v83, vcc
	v_cmp_le_i32_e32 vcc, v16, v218
	v_or_b32_e32 v16, 9, v237
	v_exp_f32_e32 v89, v89
	v_cndmask_b32_e32 v84, 0, v84, vcc
	v_cmp_le_i32_e32 vcc, v17, v218
	v_exp_f32_e32 v90, v90
	v_exp_f32_e32 v91, v91
	v_cndmask_b32_e32 v85, 0, v85, vcc
	v_cmp_le_i32_e32 vcc, v30, v218
	v_add_f32_e32 v221, v221, v82
	v_exp_f32_e32 v92, v92
	v_cndmask_b32_e32 v86, 0, v86, vcc
	v_cmp_le_i32_e32 vcc, v16, v218
	v_or_b32_e32 v16, 10, v237
	v_add_f32_e32 v221, v83, v221
	v_cndmask_b32_e32 v87, 0, v87, vcc
	v_cmp_le_i32_e32 vcc, v16, v218
	v_or_b32_e32 v16, 11, v237
	v_exp_f32_e32 v93, v93
	v_cndmask_b32_e32 v88, 0, v88, vcc
	v_cmp_le_i32_e32 vcc, v16, v218
	v_or_b32_e32 v16, 16, v237
	v_add_f32_e32 v221, v84, v221
	v_cndmask_b32_e32 v89, 0, v89, vcc
	v_cmp_le_i32_e32 vcc, v16, v218
	v_or_b32_e32 v16, 17, v237
	v_exp_f32_e32 v94, v94
	v_cndmask_b32_e32 v90, 0, v90, vcc
	v_cmp_le_i32_e32 vcc, v16, v218
	v_or_b32_e32 v16, 18, v237
	v_add_f32_e32 v221, v85, v221
	v_cndmask_b32_e32 v91, 0, v91, vcc
	v_cmp_le_i32_e32 vcc, v16, v218
	v_or_b32_e32 v16, 19, v237
	v_exp_f32_e32 v95, v95
	v_add_f32_e32 v221, v86, v221
	v_cndmask_b32_e32 v92, 0, v92, vcc
	v_cmp_le_i32_e32 vcc, v16, v218
	v_or_b32_e32 v16, 24, v237
	v_cvt_pk_bf16_f32 v82, v82, v83
	v_cvt_pk_bf16_f32 v83, v84, v85
	v_cvt_pk_bf16_f32 v84, v86, v87
	v_cvt_pk_bf16_f32 v85, v88, v89
	v_add_f32_e32 v221, v87, v221
	v_cndmask_b32_e32 v93, 0, v93, vcc
	v_cmp_le_i32_e32 vcc, v16, v218
	v_or_b32_e32 v16, 25, v237
	v_mfma_f32_32x32x16_bf16 v[66:81], v[134:137], v[82:85], v[66:81]
	v_add_f32_e32 v221, v88, v221
	v_cndmask_b32_e32 v94, 0, v94, vcc
	v_exp_f32_e32 v86, v96
	v_cmp_le_i32_e32 vcc, v16, v218
	v_or_b32_e32 v88, 26, v237
	v_add_f32_e32 v221, v89, v221
	v_cndmask_b32_e32 v87, 0, v95, vcc
	v_mfma_f32_32x32x16_bf16 v[50:65], v[130:133], v[82:85], v[50:65]
	v_cmp_le_i32_e32 vcc, v88, v218
	v_exp_f32_e32 v88, v97
	v_or_b32_e32 v82, 27, v237
	v_cndmask_b32_e32 v86, 0, v86, vcc
	v_cmp_le_i32_e32 vcc, v82, v218
	v_cvt_pk_bf16_f32 v82, v90, v91
	v_cvt_pk_bf16_f32 v83, v92, v93
	v_cndmask_b32_e32 v88, 0, v88, vcc
	v_cvt_pk_bf16_f32 v84, v94, v87
	v_cvt_pk_bf16_f32 v85, v86, v88
	v_add_f32_e32 v221, v90, v221
	v_add_f32_e32 v89, v91, v221
	v_mfma_f32_32x32x16_bf16 v[66:81], v[118:121], v[82:85], v[66:81]
	v_add_f32_e32 v89, v92, v89
	v_add_f32_e32 v89, v93, v89
	v_add_f32_e32 v89, v94, v89
	v_add_f32_e32 v87, v87, v89
	v_add_f32_e32 v86, v86, v87
	v_add_f32_e32 v221, v88, v86
	v_mfma_f32_32x32x16_bf16 v[50:65], v[102:105], v[82:85], v[50:65]
	s_cmp_lg_u32 s85, s86
	s_cbranch_scc1 .Lq_nl1_k2p1
	s_min_u32 s14, s88, 63
	s_nop 3
	v_readlane_b32 s30, v33, s14
	s_and_b32 s30, s30, 0xff
	s_lshl_b32 s30, s30, 13
	s_add_u32 s64, s11, s30
	s_addc_u32 s65, s12, 0
	s_add_u32 s66, s8, s30
	s_addc_u32 s67, s9, 0
	global_load_dwordx4 v[194:197], v2, s[64:65]
	global_load_dwordx4 v[190:193], v2, s[64:65] offset:1024
	global_load_dwordx4 v[186:189], v2, s[64:65] offset:2048
	global_load_dwordx4 v[182:185], v2, s[64:65] offset:3072
	global_load_dwordx4 v[134:137], v2, s[66:67]
	global_load_dwordx4 v[130:133], v2, s[66:67] offset:1024
	global_load_dwordx4 v[118:121], v2, s[66:67] offset:2048
	global_load_dwordx4 v[102:105], v2, s[66:67] offset:3072
	s_branch .Lq_nl1_k2p1
.Lq_s0n_k2p1:
	v_and_b32_e32 v82, s18, v23
	v_cmp_ne_u32_e32 vcc, 0, v82
	s_and_b64 vcc, s[94:95], vcc
	v_mov_b32 v83, 0
	v_cndmask_b32_e32 v82, v236, v222, vcc
	v_sub_f32_e32 v82, v83, v82
	v_mov_b32_e32 v83, v82
	v_mov_b32_e32 v84, v82
	v_mov_b32_e32 v85, v82
	v_mov_b32_e32 v86, v82
	v_mov_b32_e32 v87, v82
	v_mov_b32_e32 v88, v82
	v_mov_b32_e32 v89, v82
	v_mov_b32_e32 v90, v82
	v_mov_b32_e32 v91, v82
	v_mov_b32_e32 v92, v82
	v_mov_b32_e32 v93, v82
	v_mov_b32_e32 v94, v82
	v_mov_b32_e32 v95, v82
	v_mov_b32_e32 v96, v82
	v_mov_b32_e32 v97, v82
	s_nop 1
	v_mfma_f32_32x32x16_bf16 v[82:97], v[162:165], v[238:241], v[82:97]
	v_mfma_f32_32x32x16_bf16 v[82:97], v[154:157], v[242:245], v[82:97]
	v_mfma_f32_32x32x16_bf16 v[82:97], v[150:153], v[246:249], v[82:97]
	v_mfma_f32_32x32x16_bf16 v[82:97], v[158:161], v[250:253], v[82:97]
	s_waitcnt vmcnt(12)
	v_mov_b32_e32 v28, 0
	v_and_b32_e32 v34, s18, v23
	v_cmp_ne_u32_e32 vcc, 0, v34
	s_and_b64 vcc, s[94:95], vcc
	v_mov_b32 v35, 0
	v_cndmask_b32_e32 v34, v236, v222, vcc
	v_sub_f32_e32 v34, v35, v34
	v_mov_b32_e32 v35, v34
	v_mov_b32_e32 v36, v34
	v_mov_b32_e32 v37, v34
	v_mov_b32_e32 v38, v34
	v_mov_b32_e32 v39, v34
	v_mov_b32_e32 v40, v34
	v_mov_b32_e32 v41, v34
	v_mov_b32_e32 v42, v34
	v_mov_b32_e32 v43, v34
	v_mov_b32_e32 v44, v34
	v_mov_b32_e32 v45, v34
	v_mov_b32_e32 v46, v34
	v_mov_b32_e32 v47, v34
	v_mov_b32_e32 v48, v34
	v_mov_b32_e32 v49, v34
	s_nop 1
	v_mfma_f32_32x32x16_bf16 v[34:49], v[194:197], v[238:241], v[34:49]
	v_mfma_f32_32x32x16_bf16 v[34:49], v[190:193], v[242:245], v[34:49]
	v_mfma_f32_32x32x16_bf16 v[34:49], v[186:189], v[246:249], v[34:49]
	v_mfma_f32_32x32x16_bf16 v[34:49], v[182:185], v[250:253], v[34:49]
	v_exp_f32_e32 v82, v82
	v_exp_f32_e32 v83, v83
	v_exp_f32_e32 v84, v84
	v_exp_f32_e32 v85, v85
	v_exp_f32_e32 v86, v86
	v_exp_f32_e32 v87, v87
	v_exp_f32_e32 v88, v88
	v_exp_f32_e32 v89, v89
	v_exp_f32_e32 v90, v90
	v_exp_f32_e32 v91, v91
	v_add_f32_e32 v221, v221, v82
	v_exp_f32_e32 v92, v92
	v_exp_f32_e32 v34, v34
	v_add_f32_e32 v221, v83, v221
	v_exp_f32_e32 v35, v35
	v_exp_f32_e32 v93, v93
	v_exp_f32_e32 v36, v36
	v_add_f32_e32 v221, v84, v221
	v_exp_f32_e32 v37, v37
	v_exp_f32_e32 v94, v94
	v_exp_f32_e32 v38, v38
	v_add_f32_e32 v221, v85, v221
	v_exp_f32_e32 v39, v39
	v_exp_f32_e32 v95, v95
	v_exp_f32_e32 v40, v40
	v_add_f32_e32 v221, v86, v221
	v_exp_f32_e32 v41, v41
	v_cvt_pk_bf16_f32 v82, v82, v83
	v_exp_f32_e32 v42, v42
	v_cvt_pk_bf16_f32 v83, v84, v85
	v_exp_f32_e32 v43, v43
	v_cvt_pk_bf16_f32 v84, v86, v87
	v_add_f32_e32 v28, v28, v34
	v_cvt_pk_bf16_f32 v85, v88, v89
	v_exp_f32_e32 v44, v44
	v_add_f32_e32 v221, v87, v221
	v_add_f32_e32 v28, v35, v28
	v_mfma_f32_32x32x16_bf16 v[66:81], v[138:141], v[82:85], 0
	v_exp_f32_e32 v45, v45
	v_add_f32_e32 v221, v88, v221
	v_add_f32_e32 v28, v36, v28
	v_exp_f32_e32 v86, v96
	v_exp_f32_e32 v46, v46
	v_add_f32_e32 v221, v89, v221
	v_add_f32_e32 v28, v37, v28
	v_mov_b32_e32 v87, v95
	v_exp_f32_e32 v47, v47
	v_mfma_f32_32x32x16_bf16 v[50:65], v[122:125], v[82:85], 0
	v_add_f32_e32 v28, v38, v28
	v_exp_f32_e32 v88, v97
	v_cvt_pk_bf16_f32 v34, v34, v35
	v_cvt_pk_bf16_f32 v82, v90, v91
	v_cvt_pk_bf16_f32 v35, v36, v37
	v_cvt_pk_bf16_f32 v83, v92, v93
	v_cvt_pk_bf16_f32 v36, v38, v39
	v_cvt_pk_bf16_f32 v84, v94, v87
	v_cvt_pk_bf16_f32 v37, v40, v41
	v_cvt_pk_bf16_f32 v85, v86, v88
	v_add_f32_e32 v28, v39, v28
	v_add_f32_e32 v221, v90, v221
	v_mfma_f32_32x32x16_bf16 v[66:81], v[134:137], v[34:37], v[66:81]
	v_add_f32_e32 v89, v91, v221
	v_add_f32_e32 v28, v40, v28
	v_mfma_f32_32x32x16_bf16 v[66:81], v[110:113], v[82:85], v[66:81]
	v_exp_f32_e32 v38, v48
	v_add_f32_e32 v89, v92, v89
	v_add_f32_e32 v28, v41, v28
	v_add_f32_e32 v89, v93, v89
	v_mov_b32_e32 v39, v47
	v_add_f32_e32 v89, v94, v89
	v_mfma_f32_32x32x16_bf16 v[50:65], v[130:133], v[34:37], v[50:65]
	v_add_f32_e32 v87, v87, v89
	v_exp_f32_e32 v40, v49
	v_add_f32_e32 v86, v86, v87
	v_cvt_pk_bf16_f32 v34, v42, v43
	v_add_f32_e32 v221, v88, v86
	v_cvt_pk_bf16_f32 v35, v44, v45
	v_mfma_f32_32x32x16_bf16 v[50:65], v[106:109], v[82:85], v[50:65]
	v_cvt_pk_bf16_f32 v36, v46, v39
	v_cvt_pk_bf16_f32 v37, v38, v40
	v_add_f32_e32 v28, v42, v28
	v_add_f32_e32 v41, v43, v28
	v_mfma_f32_32x32x16_bf16 v[66:81], v[118:121], v[34:37], v[66:81]
	v_add_f32_e32 v41, v44, v41
	v_add_f32_e32 v41, v45, v41
	v_add_f32_e32 v41, v46, v41
	v_add_f32_e32 v39, v39, v41
	v_add_f32_e32 v38, v38, v39
	v_add_f32_e32 v28, v40, v38
	v_mfma_f32_32x32x16_bf16 v[50:65], v[102:105], v[34:37], v[50:65]
	v_add_f32_e32 v221, v221, v28
	s_cmp_lg_u32 s85, s86
	s_cbranch_scc1 .Lq_nl1_k2p1
	s_min_u32 s14, s87, 63
	s_nop 3
	v_readlane_b32 s30, v33, s14
	s_and_b32 s30, s30, 0xff
	s_lshl_b32 s30, s30, 13
	s_or_b32 s30, s30, 0x1000
	s_add_u32 s64, s11, s30
	s_addc_u32 s65, s12, 0
	s_add_u32 s66, s8, s30
	s_addc_u32 s67, s9, 0
	global_load_dwordx4 v[162:165], v2, s[64:65]
	global_load_dwordx4 v[154:157], v2, s[64:65] offset:1024
	global_load_dwordx4 v[150:153], v2, s[64:65] offset:2048
	global_load_dwordx4 v[158:161], v2, s[64:65] offset:3072
	global_load_dwordx4 v[138:141], v2, s[66:67]
	global_load_dwordx4 v[122:125], v2, s[66:67] offset:1024
	global_load_dwordx4 v[110:113], v2, s[66:67] offset:2048
	global_load_dwordx4 v[106:109], v2, s[66:67] offset:3072
	s_min_u32 s14, s88, 63
	s_nop 3
	v_readlane_b32 s30, v33, s14
	s_and_b32 s30, s30, 0xff
	s_lshl_b32 s30, s30, 13
	s_add_u32 s64, s11, s30
	s_addc_u32 s65, s12, 0
	s_add_u32 s66, s8, s30
	s_addc_u32 s67, s9, 0
	global_load_dwordx4 v[194:197], v2, s[64:65]
	global_load_dwordx4 v[190:193], v2, s[64:65] offset:1024
	global_load_dwordx4 v[186:189], v2, s[64:65] offset:2048
	global_load_dwordx4 v[182:185], v2, s[64:65] offset:3072
	global_load_dwordx4 v[134:137], v2, s[66:67]
	global_load_dwordx4 v[130:133], v2, s[66:67] offset:1024
	global_load_dwordx4 v[118:121], v2, s[66:67] offset:2048
	global_load_dwordx4 v[102:105], v2, s[66:67] offset:3072

.Lq_vend_k2:
	s_add_i32 s52, s52, 6
	s_branch .Lq_loop

.Lq_norepeat:
	s_barrier
	v_mov_b32_e32 v82, v22
	v_mad_u32_u24 v86, v226, s82, v19
	v_add_u32_e32 v87, 0x1980, v86
	v_mad_u32_u24 v88, v226, s82, v31
	v_add_u32_e32 v89, 0x1980, v88
	ds_read_b128 v[66:69], v86
	ds_read_b128 v[70:73], v86 offset:32
	ds_read_b128 v[74:77], v86 offset:64
	ds_read_b128 v[78:81], v86 offset:96
	ds_read_b128 v[50:53], v86 offset:128
	ds_read_b128 v[54:57], v86 offset:160
	ds_read_b128 v[58:61], v86 offset:192
	ds_read_b128 v[62:65], v86 offset:224
	ds_read_b32 v221, v88
	ds_read_b128 v[34:37], v87
	ds_read_b128 v[38:41], v87 offset:32
	ds_read_b128 v[42:45], v87 offset:64
	ds_read_b128 v[46:49], v87 offset:96
	ds_read_b128 v[18:21], v87 offset:128
	ds_read_b128 v[22:25], v87 offset:160
	ds_read_b128 v[26:29], v87 offset:192
	ds_read_b128 v[30:33], v87 offset:224
	ds_read_b32 v211, v89
	s_waitcnt lgkmcnt(0)
	v_mov_b32_e32 v218, v82
	v_mov_b32_e32 v102, 0
	v_mov_b32_e32 v103, 0
	v_mov_b32_e32 v104, 0
	v_mov_b32_e32 v105, 0
	ds_write_b128 v86, v[102:105]
	ds_write_b128 v86, v[102:105] offset:32
	ds_write_b128 v86, v[102:105] offset:64
	ds_write_b128 v86, v[102:105] offset:96
	ds_write_b128 v86, v[102:105] offset:128
	ds_write_b128 v86, v[102:105] offset:160
	ds_write_b128 v86, v[102:105] offset:192
	ds_write_b128 v86, v[102:105] offset:224
	ds_write_b128 v87, v[102:105]
	ds_write_b128 v87, v[102:105] offset:32
	ds_write_b128 v87, v[102:105] offset:64
	ds_write_b128 v87, v[102:105] offset:96
	ds_write_b128 v87, v[102:105] offset:128
	ds_write_b128 v87, v[102:105] offset:160
	ds_write_b128 v87, v[102:105] offset:192
	ds_write_b128 v87, v[102:105] offset:224
	ds_write_b32 v88, v102
	ds_write_b32 v89, v102
	v_mov_b32_e32 v106, 0x1800
	ds_write_b32 v106, v102
	v_lshl_add_u32 v107, v199, 2, s90
	ds_write_b32 v107, v102
